# phase 0: all 32 loads of each weight-transpose item issued before the LDS writes (W_in had one full wait per load), p->bf16 loads batched; barrier non-leaders wait on the cross-XCD release word direct
# speedup vs baseline: 1.1331x; 1.0076x over previous
; __device__ __forceinline__ void transpose_item(const float* W, int N, int col0, bf16_t* WT, int K, int drow0, int k0, LAS float* scr, int lane) {
;     ...
;     for (int i = 0; i < 32; ++i) { const int kk = 2 * i + (lane >> 5); scr[kk * 33 + (lane & 31)] = col0 >= 0 ? __builtin_nontemporal_load(W + (size_t)(k0 + kk) * N + col0 + (lane & 31)) : 0.f; }
;     asm volatile("s_waitcnt lgkmcnt(0)" ::: "memory");
.LBB0_15:
	v_lshl_add_u64 v[90:91], v[44:45], 0, s[4:5]
	v_lshl_add_u64 v[92:93], v[42:43], 0, s[4:5]
	v_lshl_add_u64 v[94:95], v[40:41], 0, s[4:5]
	v_lshl_add_u64 v[96:97], v[38:39], 0, s[4:5]
	v_lshl_add_u64 v[98:99], v[36:37], 0, s[4:5]
	v_lshl_add_u64 v[100:101], v[34:35], 0, s[4:5]
	v_lshl_add_u64 v[102:103], v[32:33], 0, s[4:5]
	v_lshl_add_u64 v[104:105], v[30:31], 0, s[4:5]
	global_load_dword v108, v[90:91], off nt
	s_nop 0
	global_load_dword v109, v[92:93], off nt
	global_load_dword v110, v[94:95], off nt
	s_nop 0
	global_load_dword v111, v[96:97], off nt
	global_load_dword v112, v[98:99], off nt
	global_load_dword v113, v[100:101], off nt
	global_load_dword v114, v[102:103], off nt
	s_nop 0
	global_load_dword v115, v[104:105], off nt
	s_add_u32 s4, s4, 0x10000
	s_addc_u32 s5, s5, 0
	v_lshl_add_u64 v[90:91], v[44:45], 0, s[4:5]
	v_lshl_add_u64 v[92:93], v[42:43], 0, s[4:5]
	v_lshl_add_u64 v[94:95], v[40:41], 0, s[4:5]
	v_lshl_add_u64 v[96:97], v[38:39], 0, s[4:5]
	v_lshl_add_u64 v[98:99], v[36:37], 0, s[4:5]
	v_lshl_add_u64 v[100:101], v[34:35], 0, s[4:5]
	v_lshl_add_u64 v[102:103], v[32:33], 0, s[4:5]
	v_lshl_add_u64 v[104:105], v[30:31], 0, s[4:5]
	global_load_dword v116, v[90:91], off nt
	s_nop 0
	global_load_dword v117, v[92:93], off nt
	global_load_dword v118, v[94:95], off nt
	s_nop 0
	global_load_dword v119, v[96:97], off nt
	global_load_dword v120, v[98:99], off nt
	global_load_dword v121, v[100:101], off nt
	global_load_dword v122, v[102:103], off nt
	s_nop 0
	global_load_dword v123, v[104:105], off nt
	s_add_u32 s4, s4, 0x10000
	s_addc_u32 s5, s5, 0
	v_lshl_add_u64 v[90:91], v[44:45], 0, s[4:5]
	v_lshl_add_u64 v[92:93], v[42:43], 0, s[4:5]
	v_lshl_add_u64 v[94:95], v[40:41], 0, s[4:5]
	v_lshl_add_u64 v[96:97], v[38:39], 0, s[4:5]
	v_lshl_add_u64 v[98:99], v[36:37], 0, s[4:5]
	v_lshl_add_u64 v[100:101], v[34:35], 0, s[4:5]
	v_lshl_add_u64 v[102:103], v[32:33], 0, s[4:5]
	v_lshl_add_u64 v[104:105], v[30:31], 0, s[4:5]
	global_load_dword v124, v[90:91], off nt
	s_nop 0
	global_load_dword v125, v[92:93], off nt
	global_load_dword v126, v[94:95], off nt
	s_nop 0
	global_load_dword v127, v[96:97], off nt
	global_load_dword v128, v[98:99], off nt
	global_load_dword v129, v[100:101], off nt
	global_load_dword v130, v[102:103], off nt
	s_nop 0
	global_load_dword v131, v[104:105], off nt
	s_add_u32 s4, s4, 0x10000
	s_addc_u32 s5, s5, 0
	v_lshl_add_u64 v[90:91], v[44:45], 0, s[4:5]
	v_lshl_add_u64 v[92:93], v[42:43], 0, s[4:5]
	v_lshl_add_u64 v[94:95], v[40:41], 0, s[4:5]
	v_lshl_add_u64 v[96:97], v[38:39], 0, s[4:5]
	v_lshl_add_u64 v[98:99], v[36:37], 0, s[4:5]
	v_lshl_add_u64 v[100:101], v[34:35], 0, s[4:5]
	v_lshl_add_u64 v[102:103], v[32:33], 0, s[4:5]
	v_lshl_add_u64 v[104:105], v[30:31], 0, s[4:5]
	global_load_dword v132, v[90:91], off nt
	s_nop 0
	global_load_dword v133, v[92:93], off nt
	global_load_dword v134, v[94:95], off nt
	s_nop 0
	global_load_dword v135, v[96:97], off nt
	global_load_dword v136, v[98:99], off nt
	global_load_dword v137, v[100:101], off nt
	global_load_dword v138, v[102:103], off nt
	s_nop 0
	global_load_dword v139, v[104:105], off nt
	s_add_u32 s4, s4, 0x10000
	s_addc_u32 s5, s5, 0
	s_waitcnt vmcnt(31)
	ds_write_b32 v2, v108
	s_waitcnt vmcnt(30)
	ds_write_b32 v2, v109 offset:264
	s_waitcnt vmcnt(29)
	ds_write_b32 v2, v110 offset:528
	s_waitcnt vmcnt(28)
	ds_write_b32 v2, v111 offset:792
	s_waitcnt vmcnt(27)
	ds_write_b32 v2, v112 offset:1056
	s_waitcnt vmcnt(26)
	ds_write_b32 v2, v113 offset:1320
	s_waitcnt vmcnt(25)
	ds_write_b32 v2, v114 offset:1584
	s_waitcnt vmcnt(24)
	ds_write_b32 v2, v115 offset:1848
	s_waitcnt vmcnt(23)
; __device__ __forceinline__ unsigned pk2(float lo, float hi) { unsigned r; asm("v_cvt_pk_bf16_f32 %0, %1, %2" : "=v"(r) : "v"(lo), "v"(hi)); return r; }
; __device__ __forceinline__ void transpose_item(const float* W, int N, int col0, bf16_t* WT, int K, int drow0, int k0, LAS float* scr, int lane) {
;     ...
;     for (int i = 0; i < 32; ++i) { const int kk = 2 * i + (lane >> 5); scr[kk * 33 + (lane & 31)] = col0 >= 0 ? __builtin_nontemporal_load(W + (size_t)(k0 + kk) * N + col0 + (lane & 31)) : 0.f; }
;     asm volatile("s_waitcnt lgkmcnt(0)" ::: "memory");
;     const int c = lane & 7;
; #pragma unroll
;     for (int j = 0; j < 4; ++j) { const int n = (lane >> 3) + 8 * j; const LAS float* s = scr + (8 * c) * 33 + n;
;         u32x4 o; o.x = pk2(s[0 * 33], s[1 * 33]); o.y = pk2(s[2 * 33], s[3 * 33]); o.z = pk2(s[4 * 33], s[5 * 33]); o.w = pk2(s[6 * 33], s[7 * 33]);
;         *(u32x4*)(WT + (size_t)(drow0 + n) * K + k0 + 8 * c) = o; }
;     asm volatile("s_waitcnt lgkmcnt(0)" ::: "memory");
	ds_write_b32 v2, v116 offset:2112
	s_waitcnt vmcnt(22)
	ds_write_b32 v2, v117 offset:2376
	s_waitcnt vmcnt(21)
	ds_write_b32 v2, v118 offset:2640
	s_waitcnt vmcnt(20)
	ds_write_b32 v2, v119 offset:2904
	s_waitcnt vmcnt(19)
	ds_write_b32 v2, v120 offset:3168
	s_waitcnt vmcnt(18)
	ds_write_b32 v2, v121 offset:3432
	s_waitcnt vmcnt(17)
	ds_write_b32 v2, v122 offset:3696
	s_waitcnt vmcnt(16)
	ds_write_b32 v2, v123 offset:3960
	s_waitcnt vmcnt(15)
	ds_write_b32 v2, v124 offset:4224
	s_waitcnt vmcnt(14)
	ds_write_b32 v2, v125 offset:4488
	s_waitcnt vmcnt(13)
	ds_write_b32 v2, v126 offset:4752
	s_waitcnt vmcnt(12)
	ds_write_b32 v2, v127 offset:5016
	s_waitcnt vmcnt(11)
	ds_write_b32 v2, v128 offset:5280
	s_waitcnt vmcnt(10)
	ds_write_b32 v2, v129 offset:5544
	s_waitcnt vmcnt(9)
	ds_write_b32 v2, v130 offset:5808
	s_waitcnt vmcnt(8)
	ds_write_b32 v2, v131 offset:6072
	s_waitcnt vmcnt(7)
	ds_write_b32 v2, v132 offset:6336
	s_waitcnt vmcnt(6)
	ds_write_b32 v2, v133 offset:6600
	s_waitcnt vmcnt(5)
	ds_write_b32 v2, v134 offset:6864
	s_waitcnt vmcnt(4)
	ds_write_b32 v2, v135 offset:7128
	s_waitcnt vmcnt(3)
	ds_write_b32 v2, v136 offset:7392
	s_waitcnt vmcnt(2)
	ds_write_b32 v2, v137 offset:7656
	s_waitcnt vmcnt(1)
	ds_write_b32 v2, v138 offset:7920
	s_waitcnt vmcnt(0)
	ds_write_b32 v2, v139 offset:8184
	v_add_u32_e32 v2, 0x2100, v2
	s_waitcnt lgkmcnt(0)
	ds_read2_b32 v[34:35], v48 offset0:33 offset1:41
	ds_read2_b32 v[36:37], v48 offset1:8
	ds_read2_b32 v[38:39], v48 offset0:66 offset1:74
	ds_read2_b32 v[40:41], v48 offset0:99 offset1:107
	ds_read2_b32 v[42:43], v48 offset0:132 offset1:140
	ds_read2_b32 v[44:45], v48 offset0:165 offset1:173
	ds_read2_b32 v[90:91], v48 offset0:198 offset1:206
	ds_read2_b32 v[92:93], v48 offset0:231 offset1:239
	s_and_b32 s4, s15, 0x7fffffc0
	s_add_i32 s10, s4, 0xffffcc00
	v_or_b32_e32 v2, s14, v47
	v_lshl_add_u64 v[94:95], s[10:11], 1, v[6:7]
	v_lshlrev_b32_e32 v2, 11, v2
	v_lshl_add_u64 v[96:97], v[94:95], 0, v[2:3]
	s_waitcnt lgkmcnt(6)
	v_cvt_pk_bf16_f32 v30, v36, v34
	s_waitcnt lgkmcnt(4)
	v_cvt_pk_bf16_f32 v31, v38, v40
	s_waitcnt lgkmcnt(2)
	v_cvt_pk_bf16_f32 v32, v42, v44
	s_waitcnt lgkmcnt(0)
	v_cvt_pk_bf16_f32 v33, v90, v92
	global_store_dwordx4 v[96:97], v[30:33], off
	v_or_b32_e32 v2, s14, v49
	v_lshlrev_b32_e32 v2, 11, v2
	v_cvt_pk_bf16_f32 v30, v37, v35
	v_cvt_pk_bf16_f32 v31, v39, v41
	v_cvt_pk_bf16_f32 v32, v43, v45
	v_cvt_pk_bf16_f32 v33, v91, v93
	ds_read2_b32 v[36:37], v48 offset0:16 offset1:24
	ds_read2_b32 v[38:39], v48 offset0:49 offset1:57
	ds_read2_b32 v[40:41], v48 offset0:82 offset1:90
	ds_read2_b32 v[42:43], v48 offset0:115 offset1:123
	ds_read2_b32 v[44:45], v48 offset0:148 offset1:156
	ds_read2_b32 v[90:91], v48 offset0:181 offset1:189
	ds_read2_b32 v[92:93], v48 offset0:214 offset1:222
	ds_read2_b32 v[96:97], v48 offset0:247 offset1:255
	v_lshl_add_u64 v[34:35], v[94:95], 0, v[2:3]
	v_or_b32_e32 v2, s14, v50
	v_lshlrev_b32_e32 v2, 11, v2
	global_store_dwordx4 v[34:35], v[30:33], off
	v_lshl_add_u64 v[34:35], v[94:95], 0, v[2:3]
	v_or_b32_e32 v2, s14, v51
	v_lshlrev_b32_e32 v2, 11, v2
	s_waitcnt lgkmcnt(6)
	v_cvt_pk_bf16_f32 v30, v36, v38
	s_waitcnt lgkmcnt(4)
	v_cvt_pk_bf16_f32 v31, v40, v42
	s_waitcnt lgkmcnt(2)
	v_cvt_pk_bf16_f32 v32, v44, v90
	s_waitcnt lgkmcnt(0)
	v_cvt_pk_bf16_f32 v33, v92, v96
	global_store_dwordx4 v[34:35], v[30:33], off
	v_lshl_add_u64 v[34:35], v[94:95], 0, v[2:3]
	s_mov_b64 s[4:5], 0
	v_cvt_pk_bf16_f32 v30, v37, v39
	v_cvt_pk_bf16_f32 v31, v41, v43
	v_cvt_pk_bf16_f32 v32, v45, v91
	v_cvt_pk_bf16_f32 v33, v93, v97
	global_store_dwordx4 v[34:35], v[30:33], off
	s_waitcnt lgkmcnt(0)

; __device__ __forceinline__ void transpose_item(const float* W, int N, int col0, bf16_t* WT, int K, int drow0, int k0, LAS float* scr, int lane) {
;     ...
;     for (int i = 0; i < 32; ++i) { const int kk = 2 * i + (lane >> 5); scr[kk * 33 + (lane & 31)] = col0 >= 0 ? __builtin_nontemporal_load(W + (size_t)(k0 + kk) * N + col0 + (lane & 31)) : 0.f; }
;     asm volatile("s_waitcnt lgkmcnt(0)" ::: "memory");
.LBB0_19:
	v_lshl_add_u64 v[90:91], v[44:45], 0, s[4:5]
	v_lshl_add_u64 v[92:93], v[42:43], 0, s[4:5]
	v_lshl_add_u64 v[94:95], v[40:41], 0, s[4:5]
	v_lshl_add_u64 v[96:97], v[38:39], 0, s[4:5]
	v_lshl_add_u64 v[98:99], v[36:37], 0, s[4:5]
	v_lshl_add_u64 v[100:101], v[34:35], 0, s[4:5]
	v_lshl_add_u64 v[102:103], v[32:33], 0, s[4:5]
	v_lshl_add_u64 v[104:105], v[30:31], 0, s[4:5]
	global_load_dword v108, v[90:91], off nt
	s_nop 0
	global_load_dword v109, v[92:93], off nt
	global_load_dword v110, v[94:95], off nt
	s_nop 0
	global_load_dword v111, v[96:97], off nt
	global_load_dword v112, v[98:99], off nt
	global_load_dword v113, v[100:101], off nt
	global_load_dword v114, v[102:103], off nt
	s_nop 0
	global_load_dword v115, v[104:105], off nt
	s_add_u32 s4, s4, 0x10000
	s_addc_u32 s5, s5, 0
	v_lshl_add_u64 v[90:91], v[44:45], 0, s[4:5]
	v_lshl_add_u64 v[92:93], v[42:43], 0, s[4:5]
	v_lshl_add_u64 v[94:95], v[40:41], 0, s[4:5]
	v_lshl_add_u64 v[96:97], v[38:39], 0, s[4:5]
	v_lshl_add_u64 v[98:99], v[36:37], 0, s[4:5]
	v_lshl_add_u64 v[100:101], v[34:35], 0, s[4:5]
	v_lshl_add_u64 v[102:103], v[32:33], 0, s[4:5]
	v_lshl_add_u64 v[104:105], v[30:31], 0, s[4:5]
	global_load_dword v116, v[90:91], off nt
	s_nop 0
	global_load_dword v117, v[92:93], off nt
	global_load_dword v118, v[94:95], off nt
	s_nop 0
	global_load_dword v119, v[96:97], off nt
	global_load_dword v120, v[98:99], off nt
	global_load_dword v121, v[100:101], off nt
	global_load_dword v122, v[102:103], off nt
	s_nop 0
	global_load_dword v123, v[104:105], off nt
	s_add_u32 s4, s4, 0x10000
	s_addc_u32 s5, s5, 0
	v_lshl_add_u64 v[90:91], v[44:45], 0, s[4:5]
	v_lshl_add_u64 v[92:93], v[42:43], 0, s[4:5]
	v_lshl_add_u64 v[94:95], v[40:41], 0, s[4:5]
	v_lshl_add_u64 v[96:97], v[38:39], 0, s[4:5]
	v_lshl_add_u64 v[98:99], v[36:37], 0, s[4:5]
	v_lshl_add_u64 v[100:101], v[34:35], 0, s[4:5]
	v_lshl_add_u64 v[102:103], v[32:33], 0, s[4:5]
	v_lshl_add_u64 v[104:105], v[30:31], 0, s[4:5]
	global_load_dword v124, v[90:91], off nt
	s_nop 0
	global_load_dword v125, v[92:93], off nt
	global_load_dword v126, v[94:95], off nt
	s_nop 0
	global_load_dword v127, v[96:97], off nt
	global_load_dword v128, v[98:99], off nt
	global_load_dword v129, v[100:101], off nt
	global_load_dword v130, v[102:103], off nt
	s_nop 0
	global_load_dword v131, v[104:105], off nt
	s_add_u32 s4, s4, 0x10000
	s_addc_u32 s5, s5, 0
	v_lshl_add_u64 v[90:91], v[44:45], 0, s[4:5]
	v_lshl_add_u64 v[92:93], v[42:43], 0, s[4:5]
	v_lshl_add_u64 v[94:95], v[40:41], 0, s[4:5]
	v_lshl_add_u64 v[96:97], v[38:39], 0, s[4:5]
	v_lshl_add_u64 v[98:99], v[36:37], 0, s[4:5]
	v_lshl_add_u64 v[100:101], v[34:35], 0, s[4:5]
	v_lshl_add_u64 v[102:103], v[32:33], 0, s[4:5]
	v_lshl_add_u64 v[104:105], v[30:31], 0, s[4:5]
	global_load_dword v132, v[90:91], off nt
	s_nop 0
	global_load_dword v133, v[92:93], off nt
	global_load_dword v134, v[94:95], off nt
	s_nop 0
	global_load_dword v135, v[96:97], off nt
	global_load_dword v136, v[98:99], off nt
	global_load_dword v137, v[100:101], off nt
	global_load_dword v138, v[102:103], off nt
	s_nop 0
	global_load_dword v139, v[104:105], off nt
	s_add_u32 s4, s4, 0x10000
	s_addc_u32 s5, s5, 0
	s_waitcnt vmcnt(31)
	ds_write_b32 v2, v108
	s_waitcnt vmcnt(30)
	ds_write_b32 v2, v109 offset:264
	s_waitcnt vmcnt(29)
	ds_write_b32 v2, v110 offset:528
	s_waitcnt vmcnt(28)
	ds_write_b32 v2, v111 offset:792
	s_waitcnt vmcnt(27)
	ds_write_b32 v2, v112 offset:1056
	s_waitcnt vmcnt(26)
	ds_write_b32 v2, v113 offset:1320
	s_waitcnt vmcnt(25)
	ds_write_b32 v2, v114 offset:1584
	s_waitcnt vmcnt(24)
	ds_write_b32 v2, v115 offset:1848
	s_waitcnt vmcnt(23)
; __device__ __forceinline__ unsigned pk2(float lo, float hi) { unsigned r; asm("v_cvt_pk_bf16_f32 %0, %1, %2" : "=v"(r) : "v"(lo), "v"(hi)); return r; }
; __device__ __forceinline__ void transpose_item(const float* W, int N, int col0, bf16_t* WT, int K, int drow0, int k0, LAS float* scr, int lane) {
;     ...
;     for (int i = 0; i < 32; ++i) { const int kk = 2 * i + (lane >> 5); scr[kk * 33 + (lane & 31)] = col0 >= 0 ? __builtin_nontemporal_load(W + (size_t)(k0 + kk) * N + col0 + (lane & 31)) : 0.f; }
;     asm volatile("s_waitcnt lgkmcnt(0)" ::: "memory");
;     const int c = lane & 7;
; #pragma unroll
;     for (int j = 0; j < 4; ++j) { const int n = (lane >> 3) + 8 * j; const LAS float* s = scr + (8 * c) * 33 + n;
;         u32x4 o; o.x = pk2(s[0 * 33], s[1 * 33]); o.y = pk2(s[2 * 33], s[3 * 33]); o.z = pk2(s[4 * 33], s[5 * 33]); o.w = pk2(s[6 * 33], s[7 * 33]);
;         *(u32x4*)(WT + (size_t)(drow0 + n) * K + k0 + 8 * c) = o; }
;     asm volatile("s_waitcnt lgkmcnt(0)" ::: "memory");
	ds_write_b32 v2, v116 offset:2112
	s_waitcnt vmcnt(22)
	ds_write_b32 v2, v117 offset:2376
	s_waitcnt vmcnt(21)
	ds_write_b32 v2, v118 offset:2640
	s_waitcnt vmcnt(20)
	ds_write_b32 v2, v119 offset:2904
	s_waitcnt vmcnt(19)
	ds_write_b32 v2, v120 offset:3168
	s_waitcnt vmcnt(18)
	ds_write_b32 v2, v121 offset:3432
	s_waitcnt vmcnt(17)
	ds_write_b32 v2, v122 offset:3696
	s_waitcnt vmcnt(16)
	ds_write_b32 v2, v123 offset:3960
	s_waitcnt vmcnt(15)
	ds_write_b32 v2, v124 offset:4224
	s_waitcnt vmcnt(14)
	ds_write_b32 v2, v125 offset:4488
	s_waitcnt vmcnt(13)
	ds_write_b32 v2, v126 offset:4752
	s_waitcnt vmcnt(12)
	ds_write_b32 v2, v127 offset:5016
	s_waitcnt vmcnt(11)
	ds_write_b32 v2, v128 offset:5280
	s_waitcnt vmcnt(10)
	ds_write_b32 v2, v129 offset:5544
	s_waitcnt vmcnt(9)
	ds_write_b32 v2, v130 offset:5808
	s_waitcnt vmcnt(8)
	ds_write_b32 v2, v131 offset:6072
	s_waitcnt vmcnt(7)
	ds_write_b32 v2, v132 offset:6336
	s_waitcnt vmcnt(6)
	ds_write_b32 v2, v133 offset:6600
	s_waitcnt vmcnt(5)
	ds_write_b32 v2, v134 offset:6864
	s_waitcnt vmcnt(4)
	ds_write_b32 v2, v135 offset:7128
	s_waitcnt vmcnt(3)
	ds_write_b32 v2, v136 offset:7392
	s_waitcnt vmcnt(2)
	ds_write_b32 v2, v137 offset:7656
	s_waitcnt vmcnt(1)
	ds_write_b32 v2, v138 offset:7920
	s_waitcnt vmcnt(0)
	ds_write_b32 v2, v139 offset:8184
	v_add_u32_e32 v2, 0x2100, v2
	s_waitcnt lgkmcnt(0)
	ds_read2_b32 v[34:35], v48 offset0:33 offset1:41
	ds_read2_b32 v[36:37], v48 offset1:8
	ds_read2_b32 v[38:39], v48 offset0:66 offset1:74
	ds_read2_b32 v[40:41], v48 offset0:99 offset1:107
	ds_read2_b32 v[42:43], v48 offset0:132 offset1:140
	ds_read2_b32 v[44:45], v48 offset0:165 offset1:173
	ds_read2_b32 v[90:91], v48 offset0:198 offset1:206
	ds_read2_b32 v[92:93], v48 offset0:231 offset1:239
	s_and_b32 s4, s15, 0x3fc0
	s_add_i32 s10, s4, 0xffffcd00
	v_or_b32_e32 v2, s14, v47
	v_lshl_add_u64 v[94:95], s[10:11], 1, v[8:9]
	v_lshlrev_b32_e32 v2, 9, v2
	v_lshl_add_u64 v[96:97], v[94:95], 0, v[2:3]
	s_waitcnt lgkmcnt(6)
	v_cvt_pk_bf16_f32 v30, v36, v34
	s_waitcnt lgkmcnt(4)
	v_cvt_pk_bf16_f32 v31, v38, v40
	s_waitcnt lgkmcnt(2)
	v_cvt_pk_bf16_f32 v32, v42, v44
	s_waitcnt lgkmcnt(0)
	v_cvt_pk_bf16_f32 v33, v90, v92
	global_store_dwordx4 v[96:97], v[30:33], off
	v_or_b32_e32 v2, s14, v49
	v_lshlrev_b32_e32 v2, 9, v2
	v_cvt_pk_bf16_f32 v30, v37, v35
	v_cvt_pk_bf16_f32 v31, v39, v41
	v_cvt_pk_bf16_f32 v32, v43, v45
	v_cvt_pk_bf16_f32 v33, v91, v93
	ds_read2_b32 v[36:37], v48 offset0:16 offset1:24
	ds_read2_b32 v[38:39], v48 offset0:49 offset1:57
	ds_read2_b32 v[40:41], v48 offset0:82 offset1:90
	ds_read2_b32 v[42:43], v48 offset0:115 offset1:123
	ds_read2_b32 v[44:45], v48 offset0:148 offset1:156
	ds_read2_b32 v[90:91], v48 offset0:181 offset1:189
	ds_read2_b32 v[92:93], v48 offset0:214 offset1:222
	ds_read2_b32 v[96:97], v48 offset0:247 offset1:255
	v_lshl_add_u64 v[34:35], v[94:95], 0, v[2:3]
	v_or_b32_e32 v2, s14, v50
	v_lshlrev_b32_e32 v2, 9, v2
	global_store_dwordx4 v[34:35], v[30:33], off
	v_lshl_add_u64 v[34:35], v[94:95], 0, v[2:3]
	v_or_b32_e32 v2, s14, v51
	v_lshlrev_b32_e32 v2, 9, v2
	s_waitcnt lgkmcnt(6)
	v_cvt_pk_bf16_f32 v30, v36, v38
	s_waitcnt lgkmcnt(4)
	v_cvt_pk_bf16_f32 v31, v40, v42
	s_waitcnt lgkmcnt(2)
	v_cvt_pk_bf16_f32 v32, v44, v90
	s_waitcnt lgkmcnt(0)
	v_cvt_pk_bf16_f32 v33, v92, v96
	global_store_dwordx4 v[34:35], v[30:33], off
	v_lshl_add_u64 v[34:35], v[94:95], 0, v[2:3]
	s_nop 0
	v_cvt_pk_bf16_f32 v30, v37, v39
	v_cvt_pk_bf16_f32 v31, v41, v43
	v_cvt_pk_bf16_f32 v32, v45, v91
	v_cvt_pk_bf16_f32 v33, v93, v97
	global_store_dwordx4 v[34:35], v[30:33], off
	s_waitcnt lgkmcnt(0)

; __device__ __forceinline__ void transpose_item(const float* W, int N, int col0, bf16_t* WT, int K, int drow0, int k0, LAS float* scr, int lane) {
;     ...
;     for (int i = 0; i < 32; ++i) { const int kk = 2 * i + (lane >> 5); scr[kk * 33 + (lane & 31)] = col0 >= 0 ? __builtin_nontemporal_load(W + (size_t)(k0 + kk) * N + col0 + (lane & 31)) : 0.f; }
;     asm volatile("s_waitcnt lgkmcnt(0)" ::: "memory");
.LBB0_24:
	v_lshl_add_u64 v[90:91], v[44:45], 0, s[4:5]
	v_lshl_add_u64 v[92:93], v[42:43], 0, s[4:5]
	v_lshl_add_u64 v[94:95], v[40:41], 0, s[4:5]
	v_lshl_add_u64 v[96:97], v[38:39], 0, s[4:5]
	v_lshl_add_u64 v[98:99], v[36:37], 0, s[4:5]
	v_lshl_add_u64 v[100:101], v[34:35], 0, s[4:5]
	v_lshl_add_u64 v[102:103], v[32:33], 0, s[4:5]
	v_lshl_add_u64 v[104:105], v[30:31], 0, s[4:5]
	global_load_dword v108, v[90:91], off nt
	s_nop 0
	global_load_dword v109, v[92:93], off nt
	global_load_dword v110, v[94:95], off nt
	s_nop 0
	global_load_dword v111, v[96:97], off nt
	global_load_dword v112, v[98:99], off nt
	global_load_dword v113, v[100:101], off nt
	global_load_dword v114, v[102:103], off nt
	s_nop 0
	global_load_dword v115, v[104:105], off nt
	s_add_u32 s4, s4, 0x10000
	s_addc_u32 s5, s5, 0
	v_lshl_add_u64 v[90:91], v[44:45], 0, s[4:5]
	v_lshl_add_u64 v[92:93], v[42:43], 0, s[4:5]
	v_lshl_add_u64 v[94:95], v[40:41], 0, s[4:5]
	v_lshl_add_u64 v[96:97], v[38:39], 0, s[4:5]
	v_lshl_add_u64 v[98:99], v[36:37], 0, s[4:5]
	v_lshl_add_u64 v[100:101], v[34:35], 0, s[4:5]
	v_lshl_add_u64 v[102:103], v[32:33], 0, s[4:5]
	v_lshl_add_u64 v[104:105], v[30:31], 0, s[4:5]
	global_load_dword v116, v[90:91], off nt
	s_nop 0
	global_load_dword v117, v[92:93], off nt
	global_load_dword v118, v[94:95], off nt
	s_nop 0
	global_load_dword v119, v[96:97], off nt
	global_load_dword v120, v[98:99], off nt
	global_load_dword v121, v[100:101], off nt
	global_load_dword v122, v[102:103], off nt
	s_nop 0
	global_load_dword v123, v[104:105], off nt
	s_add_u32 s4, s4, 0x10000
	s_addc_u32 s5, s5, 0
	v_lshl_add_u64 v[90:91], v[44:45], 0, s[4:5]
	v_lshl_add_u64 v[92:93], v[42:43], 0, s[4:5]
	v_lshl_add_u64 v[94:95], v[40:41], 0, s[4:5]
	v_lshl_add_u64 v[96:97], v[38:39], 0, s[4:5]
	v_lshl_add_u64 v[98:99], v[36:37], 0, s[4:5]
	v_lshl_add_u64 v[100:101], v[34:35], 0, s[4:5]
	v_lshl_add_u64 v[102:103], v[32:33], 0, s[4:5]
	v_lshl_add_u64 v[104:105], v[30:31], 0, s[4:5]
	global_load_dword v124, v[90:91], off nt
	s_nop 0
	global_load_dword v125, v[92:93], off nt
	global_load_dword v126, v[94:95], off nt
	s_nop 0
	global_load_dword v127, v[96:97], off nt
	global_load_dword v128, v[98:99], off nt
	global_load_dword v129, v[100:101], off nt
	global_load_dword v130, v[102:103], off nt
	s_nop 0
	global_load_dword v131, v[104:105], off nt
	s_add_u32 s4, s4, 0x10000
	s_addc_u32 s5, s5, 0
	v_lshl_add_u64 v[90:91], v[44:45], 0, s[4:5]
	v_lshl_add_u64 v[92:93], v[42:43], 0, s[4:5]
	v_lshl_add_u64 v[94:95], v[40:41], 0, s[4:5]
	v_lshl_add_u64 v[96:97], v[38:39], 0, s[4:5]
	v_lshl_add_u64 v[98:99], v[36:37], 0, s[4:5]
	v_lshl_add_u64 v[100:101], v[34:35], 0, s[4:5]
	v_lshl_add_u64 v[102:103], v[32:33], 0, s[4:5]
	v_lshl_add_u64 v[104:105], v[30:31], 0, s[4:5]
	global_load_dword v132, v[90:91], off nt
	s_nop 0
	global_load_dword v133, v[92:93], off nt
	global_load_dword v134, v[94:95], off nt
	s_nop 0
	global_load_dword v135, v[96:97], off nt
	global_load_dword v136, v[98:99], off nt
	global_load_dword v137, v[100:101], off nt
	global_load_dword v138, v[102:103], off nt
	s_nop 0
	global_load_dword v139, v[104:105], off nt
	s_add_u32 s4, s4, 0x10000
	s_addc_u32 s5, s5, 0
	s_waitcnt vmcnt(31)
	ds_write_b32 v2, v108
	s_waitcnt vmcnt(30)
	ds_write_b32 v2, v109 offset:264
	s_waitcnt vmcnt(29)
	ds_write_b32 v2, v110 offset:528
	s_waitcnt vmcnt(28)
	ds_write_b32 v2, v111 offset:792
	s_waitcnt vmcnt(27)
	ds_write_b32 v2, v112 offset:1056
	s_waitcnt vmcnt(26)
	ds_write_b32 v2, v113 offset:1320
	s_waitcnt vmcnt(25)
	ds_write_b32 v2, v114 offset:1584
	s_waitcnt vmcnt(24)
	ds_write_b32 v2, v115 offset:1848
	s_waitcnt vmcnt(23)
	ds_write_b32 v2, v116 offset:2112
	s_waitcnt vmcnt(22)
; __device__ __forceinline__ unsigned pk2(float lo, float hi) { unsigned r; asm("v_cvt_pk_bf16_f32 %0, %1, %2" : "=v"(r) : "v"(lo), "v"(hi)); return r; }
; __device__ __forceinline__ void transpose_item(const float* W, int N, int col0, bf16_t* WT, int K, int drow0, int k0, LAS float* scr, int lane) {
;     ...
;     for (int i = 0; i < 32; ++i) { const int kk = 2 * i + (lane >> 5); scr[kk * 33 + (lane & 31)] = col0 >= 0 ? __builtin_nontemporal_load(W + (size_t)(k0 + kk) * N + col0 + (lane & 31)) : 0.f; }
;     asm volatile("s_waitcnt lgkmcnt(0)" ::: "memory");
;     const int c = lane & 7;
; #pragma unroll
;     for (int j = 0; j < 4; ++j) { const int n = (lane >> 3) + 8 * j; const LAS float* s = scr + (8 * c) * 33 + n;
;         u32x4 o; o.x = pk2(s[0 * 33], s[1 * 33]); o.y = pk2(s[2 * 33], s[3 * 33]); o.z = pk2(s[4 * 33], s[5 * 33]); o.w = pk2(s[6 * 33], s[7 * 33]);
;         *(u32x4*)(WT + (size_t)(drow0 + n) * K + k0 + 8 * c) = o; }
;     asm volatile("s_waitcnt lgkmcnt(0)" ::: "memory");
	ds_write_b32 v2, v117 offset:2376
	s_waitcnt vmcnt(21)
	ds_write_b32 v2, v118 offset:2640
	s_waitcnt vmcnt(20)
	ds_write_b32 v2, v119 offset:2904
	s_waitcnt vmcnt(19)
	ds_write_b32 v2, v120 offset:3168
	s_waitcnt vmcnt(18)
	ds_write_b32 v2, v121 offset:3432
	s_waitcnt vmcnt(17)
	ds_write_b32 v2, v122 offset:3696
	s_waitcnt vmcnt(16)
	ds_write_b32 v2, v123 offset:3960
	s_waitcnt vmcnt(15)
	ds_write_b32 v2, v124 offset:4224
	s_waitcnt vmcnt(14)
	ds_write_b32 v2, v125 offset:4488
	s_waitcnt vmcnt(13)
	ds_write_b32 v2, v126 offset:4752
	s_waitcnt vmcnt(12)
	ds_write_b32 v2, v127 offset:5016
	s_waitcnt vmcnt(11)
	ds_write_b32 v2, v128 offset:5280
	s_waitcnt vmcnt(10)
	ds_write_b32 v2, v129 offset:5544
	s_waitcnt vmcnt(9)
	ds_write_b32 v2, v130 offset:5808
	s_waitcnt vmcnt(8)
	ds_write_b32 v2, v131 offset:6072
	s_waitcnt vmcnt(7)
	ds_write_b32 v2, v132 offset:6336
	s_waitcnt vmcnt(6)
	ds_write_b32 v2, v133 offset:6600
	s_waitcnt vmcnt(5)
	ds_write_b32 v2, v134 offset:6864
	s_waitcnt vmcnt(4)
	ds_write_b32 v2, v135 offset:7128
	s_waitcnt vmcnt(3)
	ds_write_b32 v2, v136 offset:7392
	s_waitcnt vmcnt(2)
	ds_write_b32 v2, v137 offset:7656
	s_waitcnt vmcnt(1)
	ds_write_b32 v2, v138 offset:7920
	s_waitcnt vmcnt(0)
	ds_write_b32 v2, v139 offset:8184
	v_add_u32_e32 v2, 0x2100, v2
	s_and_b32 s4, s15, 0x3fc0
	s_waitcnt lgkmcnt(0)
	v_or_b32_e32 v2, s14, v47
	s_add_i32 s10, s4, 0xffffd800
	ds_read2_b32 v[34:35], v48 offset0:33 offset1:41
	ds_read2_b32 v[36:37], v48 offset1:8
	ds_read2_b32 v[38:39], v48 offset0:66 offset1:74
	ds_read2_b32 v[40:41], v48 offset0:99 offset1:107
	ds_read2_b32 v[42:43], v48 offset0:132 offset1:140
	ds_read2_b32 v[44:45], v48 offset0:165 offset1:173
	ds_read2_b32 v[90:91], v48 offset0:198 offset1:206
	ds_read2_b32 v[92:93], v48 offset0:231 offset1:239
	v_mul_u32_u24_e32 v2, 0xb00, v2
	v_lshl_add_u64 v[94:95], s[10:11], 1, v[10:11]
	v_lshlrev_b32_e32 v2, 1, v2
	v_lshl_add_u64 v[96:97], v[94:95], 0, v[2:3]
	v_or_b32_e32 v2, s14, v49
	v_mul_u32_u24_e32 v2, 0xb00, v2
	s_waitcnt lgkmcnt(6)
	v_cvt_pk_bf16_f32 v30, v36, v34
	v_lshlrev_b32_e32 v2, 1, v2
	s_waitcnt lgkmcnt(4)
	v_cvt_pk_bf16_f32 v31, v38, v40
	s_waitcnt lgkmcnt(2)
	v_cvt_pk_bf16_f32 v32, v42, v44
	s_waitcnt lgkmcnt(0)
	v_cvt_pk_bf16_f32 v33, v90, v92
	global_store_dwordx4 v[96:97], v[30:33], off
	s_nop 1
	v_cvt_pk_bf16_f32 v30, v37, v35
	v_lshl_add_u64 v[34:35], v[94:95], 0, v[2:3]
	v_or_b32_e32 v2, s14, v50
	v_cvt_pk_bf16_f32 v31, v39, v41
	v_cvt_pk_bf16_f32 v32, v43, v45
	v_cvt_pk_bf16_f32 v33, v91, v93
	ds_read2_b32 v[36:37], v48 offset0:16 offset1:24
	ds_read2_b32 v[38:39], v48 offset0:49 offset1:57
	ds_read2_b32 v[40:41], v48 offset0:82 offset1:90
	ds_read2_b32 v[42:43], v48 offset0:115 offset1:123
	ds_read2_b32 v[44:45], v48 offset0:148 offset1:156
	ds_read2_b32 v[90:91], v48 offset0:181 offset1:189
	ds_read2_b32 v[92:93], v48 offset0:214 offset1:222
	ds_read2_b32 v[96:97], v48 offset0:247 offset1:255
	v_mul_u32_u24_e32 v2, 0xb00, v2
	v_lshlrev_b32_e32 v2, 1, v2
	global_store_dwordx4 v[34:35], v[30:33], off
	v_lshl_add_u64 v[34:35], v[94:95], 0, v[2:3]
	v_or_b32_e32 v2, s14, v51
	v_mul_u32_u24_e32 v2, 0xb00, v2
	v_lshlrev_b32_e32 v2, 1, v2
	s_waitcnt lgkmcnt(6)
	v_cvt_pk_bf16_f32 v30, v36, v38
	s_waitcnt lgkmcnt(4)
	v_cvt_pk_bf16_f32 v31, v40, v42
	s_waitcnt lgkmcnt(2)
	v_cvt_pk_bf16_f32 v32, v44, v90
	s_waitcnt lgkmcnt(0)
	v_cvt_pk_bf16_f32 v33, v92, v96
	global_store_dwordx4 v[34:35], v[30:33], off
	v_lshl_add_u64 v[34:35], v[94:95], 0, v[2:3]
	s_nop 0
	v_cvt_pk_bf16_f32 v30, v37, v39
	v_cvt_pk_bf16_f32 v31, v41, v43
	v_cvt_pk_bf16_f32 v32, v45, v91
	v_cvt_pk_bf16_f32 v33, v93, v97
	global_store_dwordx4 v[34:35], v[30:33], off
	s_waitcnt lgkmcnt(0)

; __device__ __forceinline__ void transpose_item(const float* W, int N, int col0, bf16_t* WT, int K, int drow0, int k0, LAS float* scr, int lane) {
;     ...
;     for (int i = 0; i < 32; ++i) { const int kk = 2 * i + (lane >> 5); scr[kk * 33 + (lane & 31)] = col0 >= 0 ? __builtin_nontemporal_load(W + (size_t)(k0 + kk) * N + col0 + (lane & 31)) : 0.f; }
;     asm volatile("s_waitcnt lgkmcnt(0)" ::: "memory");
.LBB0_29:
	v_lshl_add_u64 v[40:41], v[38:39], 0, s[4:5]
	v_add_co_u32_e32 v94, vcc, 0x5000, v40
	global_load_dword v108, v[40:41], off nt
	s_nop 0
	v_addc_co_u32_e32 v95, vcc, 0, v41, vcc
	v_add_co_u32_e32 v96, vcc, 0xb000, v40
	global_load_dword v109, v[94:95], off offset:2048 nt
	s_nop 0
	v_addc_co_u32_e32 v97, vcc, 0, v41, vcc
	v_add_co_u32_e32 v40, vcc, 0x10000, v40
	v_lshl_add_u64 v[42:43], v[36:37], 0, s[4:5]
	v_lshl_add_u64 v[44:45], v[34:35], 0, s[4:5]
	v_addc_co_u32_e32 v41, vcc, 0, v41, vcc
	v_lshl_add_u64 v[90:91], v[32:33], 0, s[4:5]
	v_lshl_add_u64 v[92:93], v[30:31], 0, s[4:5]
	global_load_dword v110, v[96:97], off nt
	s_nop 0
	global_load_dword v111, v[40:41], off offset:2048 nt
	s_nop 0
	global_load_dword v112, v[42:43], off nt
	s_nop 0
	global_load_dword v113, v[44:45], off nt
	global_load_dword v114, v[90:91], off nt
	s_nop 0
	global_load_dword v115, v[92:93], off nt
	s_add_u32 s4, s4, 0x2c000
	s_addc_u32 s5, s5, 0
	v_lshl_add_u64 v[40:41], v[38:39], 0, s[4:5]
	v_add_co_u32_e32 v94, vcc, 0x5000, v40
	global_load_dword v116, v[40:41], off nt
	s_nop 0
	v_addc_co_u32_e32 v95, vcc, 0, v41, vcc
	v_add_co_u32_e32 v96, vcc, 0xb000, v40
	global_load_dword v117, v[94:95], off offset:2048 nt
	s_nop 0
	v_addc_co_u32_e32 v97, vcc, 0, v41, vcc
	v_add_co_u32_e32 v40, vcc, 0x10000, v40
	v_lshl_add_u64 v[42:43], v[36:37], 0, s[4:5]
	v_lshl_add_u64 v[44:45], v[34:35], 0, s[4:5]
	v_addc_co_u32_e32 v41, vcc, 0, v41, vcc
	v_lshl_add_u64 v[90:91], v[32:33], 0, s[4:5]
	v_lshl_add_u64 v[92:93], v[30:31], 0, s[4:5]
	global_load_dword v118, v[96:97], off nt
	s_nop 0
	global_load_dword v119, v[40:41], off offset:2048 nt
	s_nop 0
	global_load_dword v120, v[42:43], off nt
	s_nop 0
	global_load_dword v121, v[44:45], off nt
	global_load_dword v122, v[90:91], off nt
	s_nop 0
	global_load_dword v123, v[92:93], off nt
	s_add_u32 s4, s4, 0x2c000
	s_addc_u32 s5, s5, 0
	v_lshl_add_u64 v[40:41], v[38:39], 0, s[4:5]
	v_add_co_u32_e32 v94, vcc, 0x5000, v40
	global_load_dword v124, v[40:41], off nt
	s_nop 0
	v_addc_co_u32_e32 v95, vcc, 0, v41, vcc
	v_add_co_u32_e32 v96, vcc, 0xb000, v40
	global_load_dword v125, v[94:95], off offset:2048 nt
	s_nop 0
	v_addc_co_u32_e32 v97, vcc, 0, v41, vcc
	v_add_co_u32_e32 v40, vcc, 0x10000, v40
	v_lshl_add_u64 v[42:43], v[36:37], 0, s[4:5]
	v_lshl_add_u64 v[44:45], v[34:35], 0, s[4:5]
	v_addc_co_u32_e32 v41, vcc, 0, v41, vcc
	v_lshl_add_u64 v[90:91], v[32:33], 0, s[4:5]
	v_lshl_add_u64 v[92:93], v[30:31], 0, s[4:5]
	global_load_dword v126, v[96:97], off nt
	s_nop 0
	global_load_dword v127, v[40:41], off offset:2048 nt
	s_nop 0
	global_load_dword v128, v[42:43], off nt
	s_nop 0
	global_load_dword v129, v[44:45], off nt
	global_load_dword v130, v[90:91], off nt
	s_nop 0
	global_load_dword v131, v[92:93], off nt
	s_add_u32 s4, s4, 0x2c000
	s_addc_u32 s5, s5, 0
	v_lshl_add_u64 v[40:41], v[38:39], 0, s[4:5]
	v_add_co_u32_e32 v94, vcc, 0x5000, v40
	global_load_dword v132, v[40:41], off nt
	s_nop 0
	v_addc_co_u32_e32 v95, vcc, 0, v41, vcc
	v_add_co_u32_e32 v96, vcc, 0xb000, v40
	global_load_dword v133, v[94:95], off offset:2048 nt
	s_nop 0
	v_addc_co_u32_e32 v97, vcc, 0, v41, vcc
	v_add_co_u32_e32 v40, vcc, 0x10000, v40
	v_lshl_add_u64 v[42:43], v[36:37], 0, s[4:5]
	v_lshl_add_u64 v[44:45], v[34:35], 0, s[4:5]
	v_addc_co_u32_e32 v41, vcc, 0, v41, vcc
	v_lshl_add_u64 v[90:91], v[32:33], 0, s[4:5]
	v_lshl_add_u64 v[92:93], v[30:31], 0, s[4:5]
	global_load_dword v134, v[96:97], off nt
	s_nop 0
	global_load_dword v135, v[40:41], off offset:2048 nt
	s_nop 0
	global_load_dword v136, v[42:43], off nt
	s_nop 0
	global_load_dword v137, v[44:45], off nt
	global_load_dword v138, v[90:91], off nt
	s_nop 0
	global_load_dword v139, v[92:93], off nt
	s_add_u32 s4, s4, 0x2c000
	s_addc_u32 s5, s5, 0
	s_waitcnt vmcnt(31)
	ds_write_b32 v2, v108
	s_waitcnt vmcnt(30)
	ds_write_b32 v2, v109 offset:264
	s_waitcnt vmcnt(29)
	ds_write_b32 v2, v110 offset:528
	s_waitcnt vmcnt(28)
; __device__ __forceinline__ unsigned pk2(float lo, float hi) { unsigned r; asm("v_cvt_pk_bf16_f32 %0, %1, %2" : "=v"(r) : "v"(lo), "v"(hi)); return r; }
; __device__ __forceinline__ void transpose_item(const float* W, int N, int col0, bf16_t* WT, int K, int drow0, int k0, LAS float* scr, int lane) {
;     ...
;     for (int i = 0; i < 32; ++i) { const int kk = 2 * i + (lane >> 5); scr[kk * 33 + (lane & 31)] = col0 >= 0 ? __builtin_nontemporal_load(W + (size_t)(k0 + kk) * N + col0 + (lane & 31)) : 0.f; }
;     asm volatile("s_waitcnt lgkmcnt(0)" ::: "memory");
;     const int c = lane & 7;
; #pragma unroll
;     for (int j = 0; j < 4; ++j) { const int n = (lane >> 3) + 8 * j; const LAS float* s = scr + (8 * c) * 33 + n;
;         u32x4 o; o.x = pk2(s[0 * 33], s[1 * 33]); o.y = pk2(s[2 * 33], s[3 * 33]); o.z = pk2(s[4 * 33], s[5 * 33]); o.w = pk2(s[6 * 33], s[7 * 33]);
;         *(u32x4*)(WT + (size_t)(drow0 + n) * K + k0 + 8 * c) = o; }
;     asm volatile("s_waitcnt lgkmcnt(0)" ::: "memory");
	ds_write_b32 v2, v111 offset:792
	s_waitcnt vmcnt(27)
	ds_write_b32 v2, v112 offset:1056
	s_waitcnt vmcnt(26)
	ds_write_b32 v2, v113 offset:1320
	s_waitcnt vmcnt(25)
	ds_write_b32 v2, v114 offset:1584
	s_waitcnt vmcnt(24)
	ds_write_b32 v2, v115 offset:1848
	s_waitcnt vmcnt(23)
	ds_write_b32 v2, v116 offset:2112
	s_waitcnt vmcnt(22)
	ds_write_b32 v2, v117 offset:2376
	s_waitcnt vmcnt(21)
	ds_write_b32 v2, v118 offset:2640
	s_waitcnt vmcnt(20)
	ds_write_b32 v2, v119 offset:2904
	s_waitcnt vmcnt(19)
	ds_write_b32 v2, v120 offset:3168
	s_waitcnt vmcnt(18)
	ds_write_b32 v2, v121 offset:3432
	s_waitcnt vmcnt(17)
	ds_write_b32 v2, v122 offset:3696
	s_waitcnt vmcnt(16)
	ds_write_b32 v2, v123 offset:3960
	s_waitcnt vmcnt(15)
	ds_write_b32 v2, v124 offset:4224
	s_waitcnt vmcnt(14)
	ds_write_b32 v2, v125 offset:4488
	s_waitcnt vmcnt(13)
	ds_write_b32 v2, v126 offset:4752
	s_waitcnt vmcnt(12)
	ds_write_b32 v2, v127 offset:5016
	s_waitcnt vmcnt(11)
	ds_write_b32 v2, v128 offset:5280
	s_waitcnt vmcnt(10)
	ds_write_b32 v2, v129 offset:5544
	s_waitcnt vmcnt(9)
	ds_write_b32 v2, v130 offset:5808
	s_waitcnt vmcnt(8)
	ds_write_b32 v2, v131 offset:6072
	s_waitcnt vmcnt(7)
	ds_write_b32 v2, v132 offset:6336
	s_waitcnt vmcnt(6)
	ds_write_b32 v2, v133 offset:6600
	s_waitcnt vmcnt(5)
	ds_write_b32 v2, v134 offset:6864
	s_waitcnt vmcnt(4)
	ds_write_b32 v2, v135 offset:7128
	s_waitcnt vmcnt(3)
	ds_write_b32 v2, v136 offset:7392
	s_waitcnt vmcnt(2)
	ds_write_b32 v2, v137 offset:7656
	s_waitcnt vmcnt(1)
	ds_write_b32 v2, v138 offset:7920
	s_waitcnt vmcnt(0)
	ds_write_b32 v2, v139 offset:8184
	v_add_u32_e32 v2, 0x2100, v2
	s_waitcnt lgkmcnt(0)
	ds_read2_b32 v[34:35], v48 offset0:33 offset1:41
	ds_read2_b32 v[36:37], v48 offset1:8
	ds_read2_b32 v[38:39], v48 offset0:66 offset1:74
	ds_read2_b32 v[40:41], v48 offset0:99 offset1:107
	ds_read2_b32 v[42:43], v48 offset0:132 offset1:140
	ds_read2_b32 v[44:45], v48 offset0:165 offset1:173
	ds_read2_b32 v[90:91], v48 offset0:198 offset1:206
	ds_read2_b32 v[92:93], v48 offset0:231 offset1:239
	s_and_b32 s4, 0xffff, s15
	s_lshl_b32 s10, s4, 1
	v_or_b32_e32 v2, s14, v47
	v_lshl_add_u64 v[94:95], v[12:13], 0, s[10:11]
	v_lshlrev_b32_e32 v2, 11, v2
	v_lshl_add_u64 v[96:97], v[94:95], 0, v[2:3]
	s_waitcnt lgkmcnt(6)
	v_cvt_pk_bf16_f32 v30, v36, v34
	s_waitcnt lgkmcnt(4)
	v_cvt_pk_bf16_f32 v31, v38, v40
	s_waitcnt lgkmcnt(2)
	v_cvt_pk_bf16_f32 v32, v42, v44
	s_waitcnt lgkmcnt(0)
	v_cvt_pk_bf16_f32 v33, v90, v92
	global_store_dwordx4 v[96:97], v[30:33], off
	v_or_b32_e32 v2, s14, v49
	v_lshlrev_b32_e32 v2, 11, v2
	v_cvt_pk_bf16_f32 v30, v37, v35
	v_cvt_pk_bf16_f32 v31, v39, v41
	v_cvt_pk_bf16_f32 v32, v43, v45
	v_cvt_pk_bf16_f32 v33, v91, v93
	ds_read2_b32 v[36:37], v48 offset0:16 offset1:24
	ds_read2_b32 v[38:39], v48 offset0:49 offset1:57
	ds_read2_b32 v[40:41], v48 offset0:82 offset1:90
	ds_read2_b32 v[42:43], v48 offset0:115 offset1:123
	ds_read2_b32 v[44:45], v48 offset0:148 offset1:156
	ds_read2_b32 v[90:91], v48 offset0:181 offset1:189
	ds_read2_b32 v[92:93], v48 offset0:214 offset1:222
	ds_read2_b32 v[96:97], v48 offset0:247 offset1:255
	v_lshl_add_u64 v[34:35], v[94:95], 0, v[2:3]
	v_or_b32_e32 v2, s14, v50
	v_lshlrev_b32_e32 v2, 11, v2
	global_store_dwordx4 v[34:35], v[30:33], off
	v_lshl_add_u64 v[34:35], v[94:95], 0, v[2:3]
	v_or_b32_e32 v2, s14, v51
	v_lshlrev_b32_e32 v2, 11, v2
	s_waitcnt lgkmcnt(6)
	v_cvt_pk_bf16_f32 v30, v36, v38
	s_waitcnt lgkmcnt(4)
	v_cvt_pk_bf16_f32 v31, v40, v42
	s_waitcnt lgkmcnt(2)
	v_cvt_pk_bf16_f32 v32, v44, v90
	s_waitcnt lgkmcnt(0)
	v_cvt_pk_bf16_f32 v33, v92, v96
	global_store_dwordx4 v[34:35], v[30:33], off
	v_lshl_add_u64 v[34:35], v[94:95], 0, v[2:3]
	s_nop 0
	v_cvt_pk_bf16_f32 v30, v37, v39
	v_cvt_pk_bf16_f32 v31, v41, v43
	v_cvt_pk_bf16_f32 v32, v45, v91
	v_cvt_pk_bf16_f32 v33, v93, v97
	global_store_dwordx4 v[34:35], v[30:33], off
	s_waitcnt lgkmcnt(0)

; __device__ __forceinline__ void transpose_item(const float* W, int N, int col0, bf16_t* WT, int K, int drow0, int k0, LAS float* scr, int lane) {
;     ...
;     for (int i = 0; i < 32; ++i) { const int kk = 2 * i + (lane >> 5); scr[kk * 33 + (lane & 31)] = col0 >= 0 ? __builtin_nontemporal_load(W + (size_t)(k0 + kk) * N + col0 + (lane & 31)) : 0.f; }
;     asm volatile("s_waitcnt lgkmcnt(0)" ::: "memory");
.LBB0_34:
	v_lshl_add_u64 v[90:91], v[44:45], 0, s[4:5]
	v_lshl_add_u64 v[92:93], v[42:43], 0, s[4:5]
	v_lshl_add_u64 v[94:95], v[40:41], 0, s[4:5]
	v_lshl_add_u64 v[96:97], v[38:39], 0, s[4:5]
	v_lshl_add_u64 v[98:99], v[36:37], 0, s[4:5]
	v_lshl_add_u64 v[100:101], v[34:35], 0, s[4:5]
	v_lshl_add_u64 v[102:103], v[32:33], 0, s[4:5]
	v_lshl_add_u64 v[104:105], v[30:31], 0, s[4:5]
	global_load_dword v108, v[90:91], off nt
	s_nop 0
	global_load_dword v109, v[92:93], off nt
	global_load_dword v110, v[94:95], off nt
	s_nop 0
	global_load_dword v111, v[96:97], off nt
	global_load_dword v112, v[98:99], off nt
	global_load_dword v113, v[100:101], off nt
	global_load_dword v114, v[102:103], off nt
	s_nop 0
	global_load_dword v115, v[104:105], off nt
	s_add_u32 s4, s4, 0x10000
	s_addc_u32 s5, s5, 0
	v_lshl_add_u64 v[90:91], v[44:45], 0, s[4:5]
	v_lshl_add_u64 v[92:93], v[42:43], 0, s[4:5]
	v_lshl_add_u64 v[94:95], v[40:41], 0, s[4:5]
	v_lshl_add_u64 v[96:97], v[38:39], 0, s[4:5]
	v_lshl_add_u64 v[98:99], v[36:37], 0, s[4:5]
	v_lshl_add_u64 v[100:101], v[34:35], 0, s[4:5]
	v_lshl_add_u64 v[102:103], v[32:33], 0, s[4:5]
	v_lshl_add_u64 v[104:105], v[30:31], 0, s[4:5]
	global_load_dword v116, v[90:91], off nt
	s_nop 0
	global_load_dword v117, v[92:93], off nt
	global_load_dword v118, v[94:95], off nt
	s_nop 0
	global_load_dword v119, v[96:97], off nt
	global_load_dword v120, v[98:99], off nt
	global_load_dword v121, v[100:101], off nt
	global_load_dword v122, v[102:103], off nt
	s_nop 0
	global_load_dword v123, v[104:105], off nt
	s_add_u32 s4, s4, 0x10000
	s_addc_u32 s5, s5, 0
	v_lshl_add_u64 v[90:91], v[44:45], 0, s[4:5]
	v_lshl_add_u64 v[92:93], v[42:43], 0, s[4:5]
	v_lshl_add_u64 v[94:95], v[40:41], 0, s[4:5]
	v_lshl_add_u64 v[96:97], v[38:39], 0, s[4:5]
	v_lshl_add_u64 v[98:99], v[36:37], 0, s[4:5]
	v_lshl_add_u64 v[100:101], v[34:35], 0, s[4:5]
	v_lshl_add_u64 v[102:103], v[32:33], 0, s[4:5]
	v_lshl_add_u64 v[104:105], v[30:31], 0, s[4:5]
	global_load_dword v124, v[90:91], off nt
	s_nop 0
	global_load_dword v125, v[92:93], off nt
	global_load_dword v126, v[94:95], off nt
	s_nop 0
	global_load_dword v127, v[96:97], off nt
	global_load_dword v128, v[98:99], off nt
	global_load_dword v129, v[100:101], off nt
	global_load_dword v130, v[102:103], off nt
	s_nop 0
	global_load_dword v131, v[104:105], off nt
	s_add_u32 s4, s4, 0x10000
	s_addc_u32 s5, s5, 0
	v_lshl_add_u64 v[90:91], v[44:45], 0, s[4:5]
	v_lshl_add_u64 v[92:93], v[42:43], 0, s[4:5]
	v_lshl_add_u64 v[94:95], v[40:41], 0, s[4:5]
	v_lshl_add_u64 v[96:97], v[38:39], 0, s[4:5]
	v_lshl_add_u64 v[98:99], v[36:37], 0, s[4:5]
	v_lshl_add_u64 v[100:101], v[34:35], 0, s[4:5]
	v_lshl_add_u64 v[102:103], v[32:33], 0, s[4:5]
	v_lshl_add_u64 v[104:105], v[30:31], 0, s[4:5]
	global_load_dword v132, v[90:91], off nt
	s_nop 0
	global_load_dword v133, v[92:93], off nt
	global_load_dword v134, v[94:95], off nt
	s_nop 0
	global_load_dword v135, v[96:97], off nt
	global_load_dword v136, v[98:99], off nt
	global_load_dword v137, v[100:101], off nt
	global_load_dword v138, v[102:103], off nt
	s_nop 0
	global_load_dword v139, v[104:105], off nt
	s_add_u32 s4, s4, 0x10000
	s_addc_u32 s5, s5, 0
	s_waitcnt vmcnt(31)
	ds_write_b32 v2, v108
	s_waitcnt vmcnt(30)
	ds_write_b32 v2, v109 offset:264
	s_waitcnt vmcnt(29)
	ds_write_b32 v2, v110 offset:528
	s_waitcnt vmcnt(28)
	ds_write_b32 v2, v111 offset:792
	s_waitcnt vmcnt(27)
	ds_write_b32 v2, v112 offset:1056
	s_waitcnt vmcnt(26)
	ds_write_b32 v2, v113 offset:1320
	s_waitcnt vmcnt(25)
	ds_write_b32 v2, v114 offset:1584
	s_waitcnt vmcnt(24)
	ds_write_b32 v2, v115 offset:1848
	s_waitcnt vmcnt(23)
; __device__ __forceinline__ unsigned pk2(float lo, float hi) { unsigned r; asm("v_cvt_pk_bf16_f32 %0, %1, %2" : "=v"(r) : "v"(lo), "v"(hi)); return r; }
; __device__ __forceinline__ void transpose_item(const float* W, int N, int col0, bf16_t* WT, int K, int drow0, int k0, LAS float* scr, int lane) {
;     ...
;     for (int i = 0; i < 32; ++i) { const int kk = 2 * i + (lane >> 5); scr[kk * 33 + (lane & 31)] = col0 >= 0 ? __builtin_nontemporal_load(W + (size_t)(k0 + kk) * N + col0 + (lane & 31)) : 0.f; }
;     asm volatile("s_waitcnt lgkmcnt(0)" ::: "memory");
;     const int c = lane & 7;
; #pragma unroll
;     for (int j = 0; j < 4; ++j) { const int n = (lane >> 3) + 8 * j; const LAS float* s = scr + (8 * c) * 33 + n;
;         u32x4 o; o.x = pk2(s[0 * 33], s[1 * 33]); o.y = pk2(s[2 * 33], s[3 * 33]); o.z = pk2(s[4 * 33], s[5 * 33]); o.w = pk2(s[6 * 33], s[7 * 33]);
;         *(u32x4*)(WT + (size_t)(drow0 + n) * K + k0 + 8 * c) = o; }
;     asm volatile("s_waitcnt lgkmcnt(0)" ::: "memory");
	ds_write_b32 v2, v116 offset:2112
	s_waitcnt vmcnt(22)
	ds_write_b32 v2, v117 offset:2376
	s_waitcnt vmcnt(21)
	ds_write_b32 v2, v118 offset:2640
	s_waitcnt vmcnt(20)
	ds_write_b32 v2, v119 offset:2904
	s_waitcnt vmcnt(19)
	ds_write_b32 v2, v120 offset:3168
	s_waitcnt vmcnt(18)
	ds_write_b32 v2, v121 offset:3432
	s_waitcnt vmcnt(17)
	ds_write_b32 v2, v122 offset:3696
	s_waitcnt vmcnt(16)
	ds_write_b32 v2, v123 offset:3960
	s_waitcnt vmcnt(15)
	ds_write_b32 v2, v124 offset:4224
	s_waitcnt vmcnt(14)
	ds_write_b32 v2, v125 offset:4488
	s_waitcnt vmcnt(13)
	ds_write_b32 v2, v126 offset:4752
	s_waitcnt vmcnt(12)
	ds_write_b32 v2, v127 offset:5016
	s_waitcnt vmcnt(11)
	ds_write_b32 v2, v128 offset:5280
	s_waitcnt vmcnt(10)
	ds_write_b32 v2, v129 offset:5544
	s_waitcnt vmcnt(9)
	ds_write_b32 v2, v130 offset:5808
	s_waitcnt vmcnt(8)
	ds_write_b32 v2, v131 offset:6072
	s_waitcnt vmcnt(7)
	ds_write_b32 v2, v132 offset:6336
	s_waitcnt vmcnt(6)
	ds_write_b32 v2, v133 offset:6600
	s_waitcnt vmcnt(5)
	ds_write_b32 v2, v134 offset:6864
	s_waitcnt vmcnt(4)
	ds_write_b32 v2, v135 offset:7128
	s_waitcnt vmcnt(3)
	ds_write_b32 v2, v136 offset:7392
	s_waitcnt vmcnt(2)
	ds_write_b32 v2, v137 offset:7656
	s_waitcnt vmcnt(1)
	ds_write_b32 v2, v138 offset:7920
	s_waitcnt vmcnt(0)
	ds_write_b32 v2, v139 offset:8184
	v_add_u32_e32 v2, 0x2100, v2
	s_waitcnt lgkmcnt(0)
	s_lshl_b32 s4, s19, 5
	s_lshl_b32 s5, s19, 1
	ds_read2_b32 v[34:35], v48 offset0:33 offset1:41
	ds_read2_b32 v[36:37], v48 offset1:8
	ds_read2_b32 v[38:39], v48 offset0:66 offset1:74
	ds_read2_b32 v[40:41], v48 offset0:99 offset1:107
	ds_read2_b32 v[42:43], v48 offset0:132 offset1:140
	ds_read2_b32 v[44:45], v48 offset0:165 offset1:173
	ds_read2_b32 v[90:91], v48 offset0:198 offset1:206
	ds_read2_b32 v[92:93], v48 offset0:231 offset1:239
	s_and_b32 s4, s4, 0x3e0
	s_and_b32 s5, s5, 0x1fc0
	s_add_i32 s10, s5, 0xfffff200
	v_or_b32_e32 v2, s4, v47
	v_lshl_add_u64 v[94:95], s[10:11], 1, v[18:19]
	v_lshlrev_b32_e32 v2, 11, v2
	v_lshl_add_u64 v[96:97], v[94:95], 0, v[2:3]
	s_waitcnt lgkmcnt(6)
	v_cvt_pk_bf16_f32 v30, v36, v34
	s_waitcnt lgkmcnt(4)
	v_cvt_pk_bf16_f32 v31, v38, v40
	s_waitcnt lgkmcnt(2)
	v_cvt_pk_bf16_f32 v32, v42, v44
	s_waitcnt lgkmcnt(0)
	v_cvt_pk_bf16_f32 v33, v90, v92
	global_store_dwordx4 v[96:97], v[30:33], off
	v_or_b32_e32 v2, s4, v49
	v_lshlrev_b32_e32 v2, 11, v2
	v_cvt_pk_bf16_f32 v30, v37, v35
	v_cvt_pk_bf16_f32 v31, v39, v41
	v_cvt_pk_bf16_f32 v32, v43, v45
	v_cvt_pk_bf16_f32 v33, v91, v93
	ds_read2_b32 v[36:37], v48 offset0:16 offset1:24
	ds_read2_b32 v[38:39], v48 offset0:49 offset1:57
	ds_read2_b32 v[40:41], v48 offset0:82 offset1:90
	ds_read2_b32 v[42:43], v48 offset0:115 offset1:123
	ds_read2_b32 v[44:45], v48 offset0:148 offset1:156
	ds_read2_b32 v[90:91], v48 offset0:181 offset1:189
	ds_read2_b32 v[92:93], v48 offset0:214 offset1:222
	ds_read2_b32 v[96:97], v48 offset0:247 offset1:255
	v_lshl_add_u64 v[34:35], v[94:95], 0, v[2:3]
	v_or_b32_e32 v2, s4, v50
	v_lshlrev_b32_e32 v2, 11, v2
	global_store_dwordx4 v[34:35], v[30:33], off
	v_lshl_add_u64 v[34:35], v[94:95], 0, v[2:3]
	v_or_b32_e32 v2, s4, v51
	v_lshlrev_b32_e32 v2, 11, v2
	s_waitcnt lgkmcnt(6)
	v_cvt_pk_bf16_f32 v30, v36, v38
	s_waitcnt lgkmcnt(4)
	v_cvt_pk_bf16_f32 v31, v40, v42
	s_waitcnt lgkmcnt(2)
	v_cvt_pk_bf16_f32 v32, v44, v90
	s_waitcnt lgkmcnt(0)
	v_cvt_pk_bf16_f32 v33, v92, v96
	global_store_dwordx4 v[34:35], v[30:33], off
	v_lshl_add_u64 v[34:35], v[94:95], 0, v[2:3]
	s_nop 0
	v_cvt_pk_bf16_f32 v30, v37, v39
	v_cvt_pk_bf16_f32 v31, v41, v43
	v_cvt_pk_bf16_f32 v32, v45, v91
	v_cvt_pk_bf16_f32 v33, v93, v97
	global_store_dwordx4 v[34:35], v[30:33], off
	s_waitcnt lgkmcnt(0)

; __device__ __forceinline__ void transpose_item(const float* W, int N, int col0, bf16_t* WT, int K, int drow0, int k0, LAS float* scr, int lane) {
;     ...
;     for (int i = 0; i < 32; ++i) { const int kk = 2 * i + (lane >> 5); scr[kk * 33 + (lane & 31)] = col0 >= 0 ? __builtin_nontemporal_load(W + (size_t)(k0 + kk) * N + col0 + (lane & 31)) : 0.f; }
;     asm volatile("s_waitcnt lgkmcnt(0)" ::: "memory");
; __device__ __forceinline__ void phase0(const Params& p, LAS unsigned char* lds, int wid, int lane) {
;     ...
;         if (r < I1) { const int kb = r / 112, nb = r % 112; transpose_item(p.in[7], 3424, nb * 32 < 3424 ? nb * 32 : -1, (bf16_t*)(ws + WS_W1T), 1024, nb * 32, kb * 64, scr, lane); continue; } r -= I1;
.LBB0_40:
	s_andn2_b64 vcc, exec, s[14:15]
	s_cbranch_vccnz .Lp0_w1_zero
	v_mad_i64_i32 v[106:107], s[22:23], v2, s18, v[30:31]
	s_mov_b32 s4, 0x6b00
	s_mov_b32 s5, 0
	global_load_dword v108, v[106:107], off nt
	v_lshl_add_u64 v[106:107], v[106:107], 0, s[4:5]
	global_load_dword v109, v[106:107], off nt
	v_lshl_add_u64 v[106:107], v[106:107], 0, s[4:5]
	global_load_dword v110, v[106:107], off nt
	v_lshl_add_u64 v[106:107], v[106:107], 0, s[4:5]
	global_load_dword v111, v[106:107], off nt
	v_lshl_add_u64 v[106:107], v[106:107], 0, s[4:5]
	global_load_dword v112, v[106:107], off nt
	v_lshl_add_u64 v[106:107], v[106:107], 0, s[4:5]
	global_load_dword v113, v[106:107], off nt
	v_lshl_add_u64 v[106:107], v[106:107], 0, s[4:5]
	global_load_dword v114, v[106:107], off nt
	v_lshl_add_u64 v[106:107], v[106:107], 0, s[4:5]
	global_load_dword v115, v[106:107], off nt
	v_lshl_add_u64 v[106:107], v[106:107], 0, s[4:5]
	global_load_dword v116, v[106:107], off nt
	v_lshl_add_u64 v[106:107], v[106:107], 0, s[4:5]
	global_load_dword v117, v[106:107], off nt
	v_lshl_add_u64 v[106:107], v[106:107], 0, s[4:5]
	global_load_dword v118, v[106:107], off nt
	v_lshl_add_u64 v[106:107], v[106:107], 0, s[4:5]
	global_load_dword v119, v[106:107], off nt
	v_lshl_add_u64 v[106:107], v[106:107], 0, s[4:5]
	global_load_dword v120, v[106:107], off nt
	v_lshl_add_u64 v[106:107], v[106:107], 0, s[4:5]
	global_load_dword v121, v[106:107], off nt
	v_lshl_add_u64 v[106:107], v[106:107], 0, s[4:5]
	global_load_dword v122, v[106:107], off nt
	v_lshl_add_u64 v[106:107], v[106:107], 0, s[4:5]
	global_load_dword v123, v[106:107], off nt
	v_lshl_add_u64 v[106:107], v[106:107], 0, s[4:5]
	global_load_dword v124, v[106:107], off nt
	v_lshl_add_u64 v[106:107], v[106:107], 0, s[4:5]
	global_load_dword v125, v[106:107], off nt
	v_lshl_add_u64 v[106:107], v[106:107], 0, s[4:5]
	global_load_dword v126, v[106:107], off nt
	v_lshl_add_u64 v[106:107], v[106:107], 0, s[4:5]
	global_load_dword v127, v[106:107], off nt
	v_lshl_add_u64 v[106:107], v[106:107], 0, s[4:5]
	global_load_dword v128, v[106:107], off nt
	v_lshl_add_u64 v[106:107], v[106:107], 0, s[4:5]
	global_load_dword v129, v[106:107], off nt
	v_lshl_add_u64 v[106:107], v[106:107], 0, s[4:5]
	global_load_dword v130, v[106:107], off nt
	v_lshl_add_u64 v[106:107], v[106:107], 0, s[4:5]
	global_load_dword v131, v[106:107], off nt
	v_lshl_add_u64 v[106:107], v[106:107], 0, s[4:5]
	global_load_dword v132, v[106:107], off nt
	v_lshl_add_u64 v[106:107], v[106:107], 0, s[4:5]
	global_load_dword v133, v[106:107], off nt
	v_lshl_add_u64 v[106:107], v[106:107], 0, s[4:5]
	global_load_dword v134, v[106:107], off nt
	v_lshl_add_u64 v[106:107], v[106:107], 0, s[4:5]
	global_load_dword v135, v[106:107], off nt
	v_lshl_add_u64 v[106:107], v[106:107], 0, s[4:5]
	global_load_dword v136, v[106:107], off nt
	v_lshl_add_u64 v[106:107], v[106:107], 0, s[4:5]
	global_load_dword v137, v[106:107], off nt
	v_lshl_add_u64 v[106:107], v[106:107], 0, s[4:5]
	global_load_dword v138, v[106:107], off nt
	v_lshl_add_u64 v[106:107], v[106:107], 0, s[4:5]
	global_load_dword v139, v[106:107], off nt
	s_waitcnt vmcnt(31)
	ds_write_b32 v32, v108
	s_waitcnt vmcnt(30)
	ds_write_b32 v32, v109 offset:264
	s_waitcnt vmcnt(29)
	ds_write_b32 v32, v110 offset:528
	s_waitcnt vmcnt(28)
	ds_write_b32 v32, v111 offset:792
	s_waitcnt vmcnt(27)
	ds_write_b32 v32, v112 offset:1056
	s_waitcnt vmcnt(26)
	ds_write_b32 v32, v113 offset:1320
	s_waitcnt vmcnt(25)
	ds_write_b32 v32, v114 offset:1584
	s_waitcnt vmcnt(24)
	ds_write_b32 v32, v115 offset:1848
	s_waitcnt vmcnt(23)
	ds_write_b32 v32, v116 offset:2112
	s_waitcnt vmcnt(22)
	ds_write_b32 v32, v117 offset:2376
	s_waitcnt vmcnt(21)
	ds_write_b32 v32, v118 offset:2640
	s_waitcnt vmcnt(20)
	ds_write_b32 v32, v119 offset:2904
	s_waitcnt vmcnt(19)
	ds_write_b32 v32, v120 offset:3168
	s_waitcnt vmcnt(18)
	ds_write_b32 v32, v121 offset:3432
	s_waitcnt vmcnt(17)
	ds_write_b32 v32, v122 offset:3696
	s_waitcnt vmcnt(16)
	ds_write_b32 v32, v123 offset:3960
	s_waitcnt vmcnt(15)
	ds_write_b32 v32, v124 offset:4224
	s_waitcnt vmcnt(14)
	ds_write_b32 v32, v125 offset:4488
	s_waitcnt vmcnt(13)
	ds_write_b32 v32, v126 offset:4752
	s_waitcnt vmcnt(12)
	ds_write_b32 v32, v127 offset:5016
	s_waitcnt vmcnt(11)
	ds_write_b32 v32, v128 offset:5280
	s_waitcnt vmcnt(10)
	ds_write_b32 v32, v129 offset:5544
	s_waitcnt vmcnt(9)
	ds_write_b32 v32, v130 offset:5808
	s_waitcnt vmcnt(8)
	ds_write_b32 v32, v131 offset:6072
	s_waitcnt vmcnt(7)
	ds_write_b32 v32, v132 offset:6336
	s_waitcnt vmcnt(6)
	ds_write_b32 v32, v133 offset:6600
	s_waitcnt vmcnt(5)
	ds_write_b32 v32, v134 offset:6864
	s_waitcnt vmcnt(4)
	ds_write_b32 v32, v135 offset:7128
	s_waitcnt vmcnt(3)
	ds_write_b32 v32, v136 offset:7392
	s_waitcnt vmcnt(2)
	ds_write_b32 v32, v137 offset:7656
	s_waitcnt vmcnt(1)
	ds_write_b32 v32, v138 offset:7920
	s_waitcnt vmcnt(0)
	ds_write_b32 v32, v139 offset:8184
	s_branch .LBB0_7
.Lp0_w1_zero:
	v_mov_b32_e32 v33, 0
	ds_write_b32 v32, v33
	ds_write_b32 v32, v33 offset:264
	ds_write_b32 v32, v33 offset:528
	ds_write_b32 v32, v33 offset:792
	ds_write_b32 v32, v33 offset:1056
	ds_write_b32 v32, v33 offset:1320
	ds_write_b32 v32, v33 offset:1584
	ds_write_b32 v32, v33 offset:1848
	ds_write_b32 v32, v33 offset:2112
	ds_write_b32 v32, v33 offset:2376
	ds_write_b32 v32, v33 offset:2640
	ds_write_b32 v32, v33 offset:2904
	ds_write_b32 v32, v33 offset:3168
	ds_write_b32 v32, v33 offset:3432
	ds_write_b32 v32, v33 offset:3696
	ds_write_b32 v32, v33 offset:3960
	ds_write_b32 v32, v33 offset:4224
	ds_write_b32 v32, v33 offset:4488
	ds_write_b32 v32, v33 offset:4752
	ds_write_b32 v32, v33 offset:5016
	ds_write_b32 v32, v33 offset:5280
	ds_write_b32 v32, v33 offset:5544
	ds_write_b32 v32, v33 offset:5808
	ds_write_b32 v32, v33 offset:6072
	ds_write_b32 v32, v33 offset:6336
	ds_write_b32 v32, v33 offset:6600
	ds_write_b32 v32, v33 offset:6864
	ds_write_b32 v32, v33 offset:7128
	ds_write_b32 v32, v33 offset:7392
	ds_write_b32 v32, v33 offset:7656
	ds_write_b32 v32, v33 offset:7920
	ds_write_b32 v32, v33 offset:8184
	s_branch .LBB0_7

; __device__ __forceinline__ unsigned pk2(float lo, float hi) { unsigned r; asm("v_cvt_pk_bf16_f32 %0, %1, %2" : "=v"(r) : "v"(lo), "v"(hi)); return r; }
; __device__ __forceinline__ void phase0(const Params& p, LAS unsigned char* lds, int wid, int lane) {
;     ...
;         const f32x4* src = (const f32x4*)p.in[1]; u32x2* dst = (u32x2*)(ws + WS_PB);
;         for (int i = gt; i < M_TOK * 256 / 4; i += GT) { const f32x4 v = __builtin_nontemporal_load(src + i); u32x2 w; w.x = pk2(v[0], v[1]); w.y = pk2(v[2], v[3]); dst[i] = w; }
.LBB0_81:
	s_or_b64 exec, exec, s[10:11]
	s_mov_b32 s0, 0x200000
	v_cmp_gt_i32_e32 vcc, s0, v2
	s_and_saveexec_b64 s[0:1], vcc
	s_cbranch_execz .LBB0_84
	v_readlane_b32 s36, v254, 5
	v_readlane_b32 s38, v254, 7
	v_readlane_b32 s39, v254, 8
	v_ashrrev_i32_e32 v3, 31, v2
	v_mov_b32_e32 v4, s38
	v_mov_b32_e32 v5, s39
	s_ashr_i32 s5, s4, 31
	v_lshl_add_u64 v[6:7], v[2:3], 3, s[58:59]
	s_mov_b64 s[12:13], 0x1e00000
	v_lshl_add_u64 v[4:5], v[2:3], 4, v[4:5]
	s_lshl_b64 s[10:11], s[4:5], 4
	v_lshl_add_u64 v[6:7], v[6:7], 0, s[12:13]
	s_lshl_b64 s[12:13], s[4:5], 3
	s_mov_b64 s[14:15], 0
	s_mov_b32 s3, 0x1fffff
	v_mov_b32_e32 v3, v2
	v_readlane_b32 s37, v254, 6
	v_readlane_b32 s40, v254, 9
	v_readlane_b32 s41, v254, 10
	v_readlane_b32 s42, v254, 11
	v_readlane_b32 s43, v254, 12
	v_readlane_b32 s44, v254, 13
	v_readlane_b32 s45, v254, 14
	v_readlane_b32 s46, v254, 15
	v_readlane_b32 s47, v254, 16
	v_readlane_b32 s48, v254, 17
	v_readlane_b32 s49, v254, 18
	v_readlane_b32 s50, v254, 19
	v_readlane_b32 s51, v254, 20
	s_cmp_lg_u32 s4, 0x20000
	s_cbranch_scc1 .LBB0_83
	global_load_dwordx4 v[108:111], v[4:5], off nt
	v_lshl_add_u64 v[4:5], v[4:5], 0, s[10:11]
	global_load_dwordx4 v[112:115], v[4:5], off nt
	v_lshl_add_u64 v[4:5], v[4:5], 0, s[10:11]
	global_load_dwordx4 v[116:119], v[4:5], off nt
	v_lshl_add_u64 v[4:5], v[4:5], 0, s[10:11]
	global_load_dwordx4 v[120:123], v[4:5], off nt
	v_lshl_add_u64 v[4:5], v[4:5], 0, s[10:11]
	global_load_dwordx4 v[124:127], v[4:5], off nt
	v_lshl_add_u64 v[4:5], v[4:5], 0, s[10:11]
	global_load_dwordx4 v[128:131], v[4:5], off nt
	v_lshl_add_u64 v[4:5], v[4:5], 0, s[10:11]
	global_load_dwordx4 v[132:135], v[4:5], off nt
	v_lshl_add_u64 v[4:5], v[4:5], 0, s[10:11]
	global_load_dwordx4 v[136:139], v[4:5], off nt
	v_lshl_add_u64 v[4:5], v[4:5], 0, s[10:11]
	global_load_dwordx4 v[140:143], v[4:5], off nt
	v_lshl_add_u64 v[4:5], v[4:5], 0, s[10:11]
	global_load_dwordx4 v[144:147], v[4:5], off nt
	v_lshl_add_u64 v[4:5], v[4:5], 0, s[10:11]
	global_load_dwordx4 v[148:151], v[4:5], off nt
	v_lshl_add_u64 v[4:5], v[4:5], 0, s[10:11]
	global_load_dwordx4 v[152:155], v[4:5], off nt
	v_lshl_add_u64 v[4:5], v[4:5], 0, s[10:11]
	global_load_dwordx4 v[156:159], v[4:5], off nt
	v_lshl_add_u64 v[4:5], v[4:5], 0, s[10:11]
	global_load_dwordx4 v[160:163], v[4:5], off nt
	v_lshl_add_u64 v[4:5], v[4:5], 0, s[10:11]
	global_load_dwordx4 v[164:167], v[4:5], off nt
	v_lshl_add_u64 v[4:5], v[4:5], 0, s[10:11]
	global_load_dwordx4 v[168:171], v[4:5], off nt
	s_waitcnt vmcnt(15)
	v_cvt_pk_bf16_f32 v172, v108, v109
	v_cvt_pk_bf16_f32 v173, v110, v111
	global_store_dwordx2 v[6:7], v[172:173], off
	v_lshl_add_u64 v[6:7], v[6:7], 0, s[12:13]
	s_waitcnt vmcnt(15)
	v_cvt_pk_bf16_f32 v174, v112, v113
	v_cvt_pk_bf16_f32 v175, v114, v115
	global_store_dwordx2 v[6:7], v[174:175], off
	v_lshl_add_u64 v[6:7], v[6:7], 0, s[12:13]
	s_waitcnt vmcnt(15)
	v_cvt_pk_bf16_f32 v176, v116, v117
	v_cvt_pk_bf16_f32 v177, v118, v119
	global_store_dwordx2 v[6:7], v[176:177], off
	v_lshl_add_u64 v[6:7], v[6:7], 0, s[12:13]
	s_waitcnt vmcnt(15)
	v_cvt_pk_bf16_f32 v178, v120, v121
	v_cvt_pk_bf16_f32 v179, v122, v123
	global_store_dwordx2 v[6:7], v[178:179], off
	v_lshl_add_u64 v[6:7], v[6:7], 0, s[12:13]
	s_waitcnt vmcnt(15)
	v_cvt_pk_bf16_f32 v180, v124, v125
	v_cvt_pk_bf16_f32 v181, v126, v127
	global_store_dwordx2 v[6:7], v[180:181], off
	v_lshl_add_u64 v[6:7], v[6:7], 0, s[12:13]
	s_waitcnt vmcnt(15)
	v_cvt_pk_bf16_f32 v182, v128, v129
	v_cvt_pk_bf16_f32 v183, v130, v131
	global_store_dwordx2 v[6:7], v[182:183], off
	v_lshl_add_u64 v[6:7], v[6:7], 0, s[12:13]
	s_waitcnt vmcnt(15)
	v_cvt_pk_bf16_f32 v184, v132, v133
	v_cvt_pk_bf16_f32 v185, v134, v135
	global_store_dwordx2 v[6:7], v[184:185], off
	v_lshl_add_u64 v[6:7], v[6:7], 0, s[12:13]
	s_waitcnt vmcnt(15)
	v_cvt_pk_bf16_f32 v186, v136, v137
	v_cvt_pk_bf16_f32 v187, v138, v139
	global_store_dwordx2 v[6:7], v[186:187], off
	v_lshl_add_u64 v[6:7], v[6:7], 0, s[12:13]
	s_waitcnt vmcnt(15)
	v_cvt_pk_bf16_f32 v188, v140, v141
	v_cvt_pk_bf16_f32 v189, v142, v143
	global_store_dwordx2 v[6:7], v[188:189], off
	v_lshl_add_u64 v[6:7], v[6:7], 0, s[12:13]
	s_waitcnt vmcnt(15)
	v_cvt_pk_bf16_f32 v190, v144, v145
	v_cvt_pk_bf16_f32 v191, v146, v147
	global_store_dwordx2 v[6:7], v[190:191], off
	v_lshl_add_u64 v[6:7], v[6:7], 0, s[12:13]
	s_waitcnt vmcnt(15)
	v_cvt_pk_bf16_f32 v192, v148, v149
	v_cvt_pk_bf16_f32 v193, v150, v151
	global_store_dwordx2 v[6:7], v[192:193], off
	v_lshl_add_u64 v[6:7], v[6:7], 0, s[12:13]
	s_waitcnt vmcnt(15)
	v_cvt_pk_bf16_f32 v194, v152, v153
	v_cvt_pk_bf16_f32 v195, v154, v155
	global_store_dwordx2 v[6:7], v[194:195], off
	v_lshl_add_u64 v[6:7], v[6:7], 0, s[12:13]
	s_waitcnt vmcnt(15)
	v_cvt_pk_bf16_f32 v196, v156, v157
	v_cvt_pk_bf16_f32 v197, v158, v159
	global_store_dwordx2 v[6:7], v[196:197], off
	v_lshl_add_u64 v[6:7], v[6:7], 0, s[12:13]
	s_waitcnt vmcnt(15)
	v_cvt_pk_bf16_f32 v198, v160, v161
	v_cvt_pk_bf16_f32 v199, v162, v163
	global_store_dwordx2 v[6:7], v[198:199], off
	v_lshl_add_u64 v[6:7], v[6:7], 0, s[12:13]
	s_waitcnt vmcnt(15)
	v_cvt_pk_bf16_f32 v200, v164, v165
	v_cvt_pk_bf16_f32 v201, v166, v167
	global_store_dwordx2 v[6:7], v[200:201], off
	v_lshl_add_u64 v[6:7], v[6:7], 0, s[12:13]
	s_waitcnt vmcnt(15)
	v_cvt_pk_bf16_f32 v202, v168, v169
	v_cvt_pk_bf16_f32 v203, v170, v171
	global_store_dwordx2 v[6:7], v[202:203], off
	s_branch .LBB0_84

; __device__ __forceinline__ unsigned xb_ld(unsigned* p)              { return __hip_atomic_load(p, __ATOMIC_RELAXED, __HIP_MEMORY_SCOPE_AGENT); }
; __device__ __forceinline__ unsigned xb_add(unsigned* p, unsigned v) { return __hip_atomic_fetch_add(p, v, __ATOMIC_RELAXED, __HIP_MEMORY_SCOPE_AGENT); }
; #define XB_SPIN(cond, bar) do { unsigned _sp = 0; while (cond) { __builtin_amdgcn_s_sleep(1); \
;     if ((++_sp & 255u) == 0u) { if (xb_ld(&(bar)[XB_TMO])) break; if (_sp > XB_SPIN_CAP) { atomicAdd(&(bar)[XB_TMO], 1u); break; } } } } while (0)
; __device__ __forceinline__ void xcd_barrier(const XcdBarrier& b) {
;     ...
;         const unsigned old = xb_add(&bar[XB_XSUB(b.x)], 1u);
;         const unsigned gen = old / nloc;
;         if (old + 1u == (gen + 1u) * nloc) {
;             __builtin_amdgcn_fence(__ATOMIC_RELEASE, "agent");
;             asm volatile("s_waitcnt vmcnt(0)" ::: "memory");
;             const unsigned og = xb_add(&bar[XB_TOP], 1u);
;             const unsigned tg = og / nx;
;             if (og + 1u == (tg + 1u) * nx) xb_add(&bar[XB_TOPGEN], 1u);
;             else XB_SPIN(xb_ld(&bar[XB_TOPGEN]) == tg, bar);
;             __builtin_amdgcn_fence(__ATOMIC_ACQUIRE, "agent");
;             xb_add(&bar[XB_XGEN(b.x)], 1u);
;             asm volatile("s_waitcnt vmcnt(0)" ::: "memory");
;         } else {
;             XB_SPIN(xb_ld(&bar[XB_XGEN(b.x)]) == gen, bar);
.LBB0_125:
	s_or_b64 exec, exec, s[8:9]
	v_cvt_f32_u32_e32 v4, v2
	s_waitcnt vmcnt(0)
	v_readfirstlane_b32 s3, v3
	v_sub_u32_e32 v3, 0, v2
	v_rcp_iflag_f32_e32 v4, v4
	v_add_u32_e32 v5, s3, v1
	v_mul_f32_e32 v4, 0x4f7ffffe, v4
	v_cvt_u32_f32_e32 v4, v4
	v_mul_lo_u32 v1, v3, v4
	v_mul_hi_u32 v1, v4, v1
	v_add_u32_e32 v1, v4, v1
	v_mul_hi_u32 v1, v5, v1
	v_mul_lo_u32 v3, v1, v2
	v_sub_u32_e32 v3, v5, v3
	v_add_u32_e32 v4, 1, v1
	v_cmp_ge_u32_e32 vcc, v3, v2
	s_nop 1
	v_cndmask_b32_e32 v1, v1, v4, vcc
	v_sub_u32_e32 v4, v3, v2
	v_cndmask_b32_e32 v3, v3, v4, vcc
	v_add_u32_e32 v4, 1, v1
	v_cmp_ge_u32_e32 vcc, v3, v2
	v_add_u32_e32 v3, 1, v5
	s_nop 0
	v_cndmask_b32_e32 v1, v1, v4, vcc
	v_mul_lo_u32 v4, v2, v1
	v_add_u32_e32 v2, v4, v2
	v_cmp_ne_u32_e32 vcc, v3, v2
	s_and_saveexec_b64 s[6:7], vcc
	s_xor_b64 s[6:7], exec, s[6:7]
	s_cbranch_execz .LBB0_139
	s_waitcnt lgkmcnt(0)
	v_mov_b32_e32 v0, 0x2f83000
	global_load_dword v0, v0, s[58:59] offset:1280 sc1
	s_add_u32 s12, s58, 0x2f83500
	s_addc_u32 s13, s59, 0
	s_waitcnt vmcnt(0)
	v_cmp_eq_u32_e32 vcc, v0, v1
	s_and_saveexec_b64 s[8:9], vcc
	s_cbranch_execz .LBB0_138
	s_add_u32 s10, s58, 0x2f80200
	s_addc_u32 s11, s59, 0
	s_mov_b32 s3, 1
	s_mov_b64 s[14:15], 0
	v_mov_b32_e32 v0, 0
	s_branch .LBB0_129

; __device__ __forceinline__ unsigned xb_ld(unsigned* p)              { return __hip_atomic_load(p, __ATOMIC_RELAXED, __HIP_MEMORY_SCOPE_AGENT); }
; __device__ __forceinline__ unsigned xb_add(unsigned* p, unsigned v) { return __hip_atomic_fetch_add(p, v, __ATOMIC_RELAXED, __HIP_MEMORY_SCOPE_AGENT); }
; #define XB_SPIN(cond, bar) do { unsigned _sp = 0; while (cond) { __builtin_amdgcn_s_sleep(1); \
;     if ((++_sp & 255u) == 0u) { if (xb_ld(&(bar)[XB_TMO])) break; if (_sp > XB_SPIN_CAP) { atomicAdd(&(bar)[XB_TMO], 1u); break; } } } } while (0)
; __device__ __forceinline__ void xcd_barrier(const XcdBarrier& b) {
;     ...
;             const unsigned og = xb_add(&bar[XB_TOP], 1u);
;             const unsigned tg = og / nx;
;             if (og + 1u == (tg + 1u) * nx) xb_add(&bar[XB_TOPGEN], 1u);
;             else XB_SPIN(xb_ld(&bar[XB_TOPGEN]) == tg, bar);
;             __builtin_amdgcn_fence(__ATOMIC_ACQUIRE, "agent");
;             xb_add(&bar[XB_XGEN(b.x)], 1u);
;             asm volatile("s_waitcnt vmcnt(0)" ::: "memory");
.LBB0_156:
	s_or_b64 exec, exec, s[6:7]
	s_mov_b64 s[6:7], exec
	v_mbcnt_lo_u32_b32 v0, s6, 0
	v_mbcnt_hi_u32_b32 v0, s7, v0
	v_cmp_eq_u32_e32 vcc, 0, v0
	s_waitcnt vmcnt(0)
	buffer_inv sc1
	s_and_saveexec_b64 s[8:9], vcc
	s_cbranch_execz .LBB0_158
	s_bcnt1_i32_b64 s3, s[6:7]
	v_mov_b32_e32 v0, 0x2000
	v_mov_b32_e32 v1, s3
.LBB0_158:
	s_or_b64 exec, exec, s[8:9]
	s_waitcnt vmcnt(0)

; __device__ __forceinline__ unsigned xb_ld(unsigned* p)              { return __hip_atomic_load(p, __ATOMIC_RELAXED, __HIP_MEMORY_SCOPE_AGENT); }
; __device__ __forceinline__ unsigned xb_add(unsigned* p, unsigned v) { return __hip_atomic_fetch_add(p, v, __ATOMIC_RELAXED, __HIP_MEMORY_SCOPE_AGENT); }
; #define XB_SPIN(cond, bar) do { unsigned _sp = 0; while (cond) { __builtin_amdgcn_s_sleep(1); \
;     if ((++_sp & 255u) == 0u) { if (xb_ld(&(bar)[XB_TMO])) break; if (_sp > XB_SPIN_CAP) { atomicAdd(&(bar)[XB_TMO], 1u); break; } } } } while (0)
; __device__ __forceinline__ void xcd_barrier(const XcdBarrier& b) {
;     ...
;             const unsigned og = xb_add(&bar[XB_TOP], 1u);
;             const unsigned tg = og / nx;
;             if (og + 1u == (tg + 1u) * nx) xb_add(&bar[XB_TOPGEN], 1u);
;             else XB_SPIN(xb_ld(&bar[XB_TOPGEN]) == tg, bar);
;             __builtin_amdgcn_fence(__ATOMIC_ACQUIRE, "agent");
;             xb_add(&bar[XB_XGEN(b.x)], 1u);
;             asm volatile("s_waitcnt vmcnt(0)" ::: "memory");
.LBB0_220:
	s_or_b64 exec, exec, s[6:7]
	s_mov_b64 s[6:7], exec
	v_mbcnt_lo_u32_b32 v0, s6, 0
	v_mbcnt_hi_u32_b32 v0, s7, v0
	v_cmp_eq_u32_e32 vcc, 0, v0
	s_waitcnt vmcnt(0)
	buffer_inv sc1
	s_and_saveexec_b64 s[8:9], vcc
	s_cbranch_execz .LBB0_222
	s_bcnt1_i32_b64 s3, s[6:7]
	v_mov_b32_e32 v0, 0x2000
	v_mov_b32_e32 v1, s3
.LBB0_222:
	s_or_b64 exec, exec, s[8:9]
	s_waitcnt vmcnt(0)

; __device__ __forceinline__ unsigned xb_ld(unsigned* p)              { return __hip_atomic_load(p, __ATOMIC_RELAXED, __HIP_MEMORY_SCOPE_AGENT); }
; __device__ __forceinline__ unsigned xb_add(unsigned* p, unsigned v) { return __hip_atomic_fetch_add(p, v, __ATOMIC_RELAXED, __HIP_MEMORY_SCOPE_AGENT); }
; #define XB_SPIN(cond, bar) do { unsigned _sp = 0; while (cond) { __builtin_amdgcn_s_sleep(1); \
;     if ((++_sp & 255u) == 0u) { if (xb_ld(&(bar)[XB_TMO])) break; if (_sp > XB_SPIN_CAP) { atomicAdd(&(bar)[XB_TMO], 1u); break; } } } } while (0)
; __device__ __forceinline__ void xcd_barrier(const XcdBarrier& b) {
;     ...
;             const unsigned og = xb_add(&bar[XB_TOP], 1u);
;             const unsigned tg = og / nx;
;             if (og + 1u == (tg + 1u) * nx) xb_add(&bar[XB_TOPGEN], 1u);
;             else XB_SPIN(xb_ld(&bar[XB_TOPGEN]) == tg, bar);
;             __builtin_amdgcn_fence(__ATOMIC_ACQUIRE, "agent");
;             xb_add(&bar[XB_XGEN(b.x)], 1u);
;             asm volatile("s_waitcnt vmcnt(0)" ::: "memory");
.LBB0_428:
	s_or_b64 exec, exec, s[6:7]
	s_mov_b64 s[6:7], exec
	v_mbcnt_lo_u32_b32 v0, s6, 0
	v_mbcnt_hi_u32_b32 v0, s7, v0
	v_cmp_eq_u32_e32 vcc, 0, v0
	s_waitcnt vmcnt(0)
	buffer_inv sc1
	s_and_saveexec_b64 s[8:9], vcc
	s_cbranch_execz .LBB0_430
	s_bcnt1_i32_b64 s3, s[6:7]
	v_mov_b32_e32 v0, 0x2000
	v_mov_b32_e32 v1, s3
.LBB0_430:
	s_or_b64 exec, exec, s[8:9]
	s_waitcnt vmcnt(0)

; __device__ __forceinline__ unsigned xb_ld(unsigned* p)              { return __hip_atomic_load(p, __ATOMIC_RELAXED, __HIP_MEMORY_SCOPE_AGENT); }
; __device__ __forceinline__ unsigned xb_add(unsigned* p, unsigned v) { return __hip_atomic_fetch_add(p, v, __ATOMIC_RELAXED, __HIP_MEMORY_SCOPE_AGENT); }
; #define XB_SPIN(cond, bar) do { unsigned _sp = 0; while (cond) { __builtin_amdgcn_s_sleep(1); \
;     if ((++_sp & 255u) == 0u) { if (xb_ld(&(bar)[XB_TMO])) break; if (_sp > XB_SPIN_CAP) { atomicAdd(&(bar)[XB_TMO], 1u); break; } } } } while (0)
; __device__ __forceinline__ void xcd_barrier(const XcdBarrier& b) {
;     ...
;             const unsigned og = xb_add(&bar[XB_TOP], 1u);
;             const unsigned tg = og / nx;
;             if (og + 1u == (tg + 1u) * nx) xb_add(&bar[XB_TOPGEN], 1u);
;             else XB_SPIN(xb_ld(&bar[XB_TOPGEN]) == tg, bar);
;             __builtin_amdgcn_fence(__ATOMIC_ACQUIRE, "agent");
;             xb_add(&bar[XB_XGEN(b.x)], 1u);
;             asm volatile("s_waitcnt vmcnt(0)" ::: "memory");
.LBB0_524:
	s_or_b64 exec, exec, s[6:7]
	s_mov_b64 s[6:7], exec
	v_mbcnt_lo_u32_b32 v0, s6, 0
	v_mbcnt_hi_u32_b32 v0, s7, v0
	v_cmp_eq_u32_e32 vcc, 0, v0
	s_waitcnt vmcnt(0)
	buffer_inv sc1
	s_and_saveexec_b64 s[8:9], vcc
	s_cbranch_execz .LBB0_526
	s_bcnt1_i32_b64 s3, s[6:7]
	v_mov_b32_e32 v0, 0x2000
	v_mov_b32_e32 v1, s3
.LBB0_526:
	s_or_b64 exec, exec, s[8:9]
	s_waitcnt vmcnt(0)

; __device__ __forceinline__ unsigned xb_ld(unsigned* p)              { return __hip_atomic_load(p, __ATOMIC_RELAXED, __HIP_MEMORY_SCOPE_AGENT); }
; __device__ __forceinline__ unsigned xb_add(unsigned* p, unsigned v) { return __hip_atomic_fetch_add(p, v, __ATOMIC_RELAXED, __HIP_MEMORY_SCOPE_AGENT); }
; #define XB_SPIN(cond, bar) do { unsigned _sp = 0; while (cond) { __builtin_amdgcn_s_sleep(1); \
;     if ((++_sp & 255u) == 0u) { if (xb_ld(&(bar)[XB_TMO])) break; if (_sp > XB_SPIN_CAP) { atomicAdd(&(bar)[XB_TMO], 1u); break; } } } } while (0)
; __device__ __forceinline__ void xcd_barrier(const XcdBarrier& b) {
;     ...
;             const unsigned og = xb_add(&bar[XB_TOP], 1u);
;             const unsigned tg = og / nx;
;             if (og + 1u == (tg + 1u) * nx) xb_add(&bar[XB_TOPGEN], 1u);
;             else XB_SPIN(xb_ld(&bar[XB_TOPGEN]) == tg, bar);
;             __builtin_amdgcn_fence(__ATOMIC_ACQUIRE, "agent");
;             xb_add(&bar[XB_XGEN(b.x)], 1u);
;             asm volatile("s_waitcnt vmcnt(0)" ::: "memory");
.LBB0_696:
	s_or_b64 exec, exec, s[6:7]
	s_mov_b64 s[6:7], exec
	v_mbcnt_lo_u32_b32 v0, s6, 0
	v_mbcnt_hi_u32_b32 v0, s7, v0
	v_cmp_eq_u32_e32 vcc, 0, v0
	s_waitcnt vmcnt(0)
	buffer_inv sc1
	s_and_saveexec_b64 s[8:9], vcc
	s_cbranch_execz .LBB0_698
	s_bcnt1_i32_b64 s3, s[6:7]
	v_mov_b32_e32 v0, 0x2000
	v_mov_b32_e32 v1, s3
.LBB0_698:
	s_or_b64 exec, exec, s[8:9]
	s_waitcnt vmcnt(0)

; __device__ __forceinline__ unsigned xb_ld(unsigned* p)              { return __hip_atomic_load(p, __ATOMIC_RELAXED, __HIP_MEMORY_SCOPE_AGENT); }
; __device__ __forceinline__ unsigned xb_add(unsigned* p, unsigned v) { return __hip_atomic_fetch_add(p, v, __ATOMIC_RELAXED, __HIP_MEMORY_SCOPE_AGENT); }
; #define XB_SPIN(cond, bar) do { unsigned _sp = 0; while (cond) { __builtin_amdgcn_s_sleep(1); \
;     if ((++_sp & 255u) == 0u) { if (xb_ld(&(bar)[XB_TMO])) break; if (_sp > XB_SPIN_CAP) { atomicAdd(&(bar)[XB_TMO], 1u); break; } } } } while (0)
; __device__ __forceinline__ void xcd_barrier(const XcdBarrier& b) {
;     ...
;             const unsigned og = xb_add(&bar[XB_TOP], 1u);
;             const unsigned tg = og / nx;
;             if (og + 1u == (tg + 1u) * nx) xb_add(&bar[XB_TOPGEN], 1u);
;             else XB_SPIN(xb_ld(&bar[XB_TOPGEN]) == tg, bar);
;             __builtin_amdgcn_fence(__ATOMIC_ACQUIRE, "agent");
;             xb_add(&bar[XB_XGEN(b.x)], 1u);
;             asm volatile("s_waitcnt vmcnt(0)" ::: "memory");
.LBB0_751:
	s_or_b64 exec, exec, s[6:7]
	s_mov_b64 s[6:7], exec
	v_mbcnt_lo_u32_b32 v0, s6, 0
	v_mbcnt_hi_u32_b32 v0, s7, v0
	v_cmp_eq_u32_e32 vcc, 0, v0
	s_waitcnt vmcnt(0)
	buffer_inv sc1
	s_and_saveexec_b64 s[8:9], vcc
	s_cbranch_execz .LBB0_753
	s_bcnt1_i32_b64 s3, s[6:7]
	v_mov_b32_e32 v0, 0x2000
	v_mov_b32_e32 v1, s3
.LBB0_753:
	s_or_b64 exec, exec, s[8:9]
	s_waitcnt vmcnt(0)

; __device__ __forceinline__ unsigned xb_add(unsigned* p, unsigned v) { return __hip_atomic_fetch_add(p, v, __ATOMIC_RELAXED, __HIP_MEMORY_SCOPE_AGENT); }
; __device__ __forceinline__ void xcd_barrier(const XcdBarrier& b) {
;     ...
;             __builtin_amdgcn_fence(__ATOMIC_ACQUIRE, "agent");
;             xb_add(&bar[XB_XGEN(b.x)], 1u);
;             asm volatile("s_waitcnt vmcnt(0)" ::: "memory");
.LBB0_841:
	s_or_b64 exec, exec, s[6:7]
	s_mov_b64 s[6:7], exec
	v_mbcnt_lo_u32_b32 v0, s6, 0
	v_mbcnt_hi_u32_b32 v0, s7, v0
	v_cmp_eq_u32_e32 vcc, 0, v0
	s_waitcnt vmcnt(0)
	buffer_inv sc1
	s_and_saveexec_b64 s[8:9], vcc
	s_cbranch_execz .LBB0_843
	s_bcnt1_i32_b64 s3, s[6:7]
	v_mov_b32_e32 v0, 0x2000
	v_mov_b32_e32 v1, s3
.LBB0_843:
	s_or_b64 exec, exec, s[8:9]
	s_waitcnt vmcnt(0)

; __device__ __forceinline__ unsigned xb_add(unsigned* p, unsigned v) { return __hip_atomic_fetch_add(p, v, __ATOMIC_RELAXED, __HIP_MEMORY_SCOPE_AGENT); }
; __device__ __forceinline__ void xcd_barrier(const XcdBarrier& b) {
;     ...
;             __builtin_amdgcn_fence(__ATOMIC_ACQUIRE, "agent");
;             xb_add(&bar[XB_XGEN(b.x)], 1u);
;             asm volatile("s_waitcnt vmcnt(0)" ::: "memory");
.LBB0_896:
	s_or_b64 exec, exec, s[6:7]
	s_mov_b64 s[6:7], exec
	v_mbcnt_lo_u32_b32 v0, s6, 0
	v_mbcnt_hi_u32_b32 v0, s7, v0
	v_cmp_eq_u32_e32 vcc, 0, v0
	s_waitcnt vmcnt(0)
	buffer_inv sc1
	s_and_saveexec_b64 s[8:9], vcc
	s_cbranch_execz .LBB0_898
	s_bcnt1_i32_b64 s3, s[6:7]
	v_mov_b32_e32 v0, 0x2000
	v_mov_b32_e32 v1, s3
.LBB0_898:
	s_or_b64 exec, exec, s[8:9]
	s_waitcnt vmcnt(0)

; __device__ __forceinline__ unsigned xb_add(unsigned* p, unsigned v) { return __hip_atomic_fetch_add(p, v, __ATOMIC_RELAXED, __HIP_MEMORY_SCOPE_AGENT); }
; __device__ __forceinline__ void xcd_barrier(const XcdBarrier& b) {
;     ...
;             __builtin_amdgcn_fence(__ATOMIC_ACQUIRE, "agent");
;             xb_add(&bar[XB_XGEN(b.x)], 1u);
;             asm volatile("s_waitcnt vmcnt(0)" ::: "memory");
.LBB0_960:
	s_or_b64 exec, exec, s[6:7]
	s_mov_b64 s[6:7], exec
	v_mbcnt_lo_u32_b32 v0, s6, 0
	v_mbcnt_hi_u32_b32 v0, s7, v0
	v_cmp_eq_u32_e32 vcc, 0, v0
	s_waitcnt vmcnt(0)
	buffer_inv sc1
	s_and_saveexec_b64 s[8:9], vcc
	s_cbranch_execz .LBB0_962
	s_bcnt1_i32_b64 s3, s[6:7]
	v_mov_b32_e32 v0, 0x2000
	v_mov_b32_e32 v1, s3
.LBB0_962:
	s_or_b64 exec, exec, s[8:9]
	s_waitcnt vmcnt(0)

; __device__ __forceinline__ unsigned xb_ld(unsigned* p)              { return __hip_atomic_load(p, __ATOMIC_RELAXED, __HIP_MEMORY_SCOPE_AGENT); }
; __device__ __forceinline__ unsigned xb_add(unsigned* p, unsigned v) { return __hip_atomic_fetch_add(p, v, __ATOMIC_RELAXED, __HIP_MEMORY_SCOPE_AGENT); }
; #define XB_SPIN(cond, bar) do { unsigned _sp = 0; while (cond) { __builtin_amdgcn_s_sleep(1); \
;     if ((++_sp & 255u) == 0u) { if (xb_ld(&(bar)[XB_TMO])) break; if (_sp > XB_SPIN_CAP) { atomicAdd(&(bar)[XB_TMO], 1u); break; } } } } while (0)
; __device__ __forceinline__ void xcd_barrier(const XcdBarrier& b) {
;     ...
;         const unsigned old = xb_add(&bar[XB_XSUB(b.x)], 1u);
;         const unsigned gen = old / nloc;
;         if (old + 1u == (gen + 1u) * nloc) {
;             __builtin_amdgcn_fence(__ATOMIC_RELEASE, "agent");
;             asm volatile("s_waitcnt vmcnt(0)" ::: "memory");
;             const unsigned og = xb_add(&bar[XB_TOP], 1u);
;             const unsigned tg = og / nx;
;             if (og + 1u == (tg + 1u) * nx) xb_add(&bar[XB_TOPGEN], 1u);
;             else XB_SPIN(xb_ld(&bar[XB_TOPGEN]) == tg, bar);
;             __builtin_amdgcn_fence(__ATOMIC_ACQUIRE, "agent");
;             xb_add(&bar[XB_XGEN(b.x)], 1u);
;             asm volatile("s_waitcnt vmcnt(0)" ::: "memory");
;         } else {
;             XB_SPIN(xb_ld(&bar[XB_XGEN(b.x)]) == gen, bar);
.LBB0_1043:
	s_or_b64 exec, exec, s[10:11]
	v_cvt_f32_u32_e32 v4, v2
	s_waitcnt vmcnt(0)
	v_readfirstlane_b32 s3, v3
	v_sub_u32_e32 v3, 0, v2
	v_rcp_iflag_f32_e32 v4, v4
	v_add_u32_e32 v5, s3, v1
	v_mul_f32_e32 v4, 0x4f7ffffe, v4
	v_cvt_u32_f32_e32 v4, v4
	v_mul_lo_u32 v1, v3, v4
	v_mul_hi_u32 v1, v4, v1
	v_add_u32_e32 v1, v4, v1
	v_mul_hi_u32 v1, v5, v1
	v_mul_lo_u32 v3, v1, v2
	v_sub_u32_e32 v3, v5, v3
	v_add_u32_e32 v4, 1, v1
	v_cmp_ge_u32_e32 vcc, v3, v2
	s_nop 1
	v_cndmask_b32_e32 v1, v1, v4, vcc
	v_sub_u32_e32 v4, v3, v2
	v_cndmask_b32_e32 v3, v3, v4, vcc
	v_add_u32_e32 v4, 1, v1
	v_cmp_ge_u32_e32 vcc, v3, v2
	v_add_u32_e32 v3, 1, v5
	s_nop 0
	v_cndmask_b32_e32 v1, v1, v4, vcc
	v_mul_lo_u32 v4, v2, v1
	v_add_u32_e32 v2, v4, v2
	v_cmp_ne_u32_e32 vcc, v3, v2
	s_and_saveexec_b64 s[6:7], vcc
	s_xor_b64 s[6:7], exec, s[6:7]
	s_cbranch_execz .LBB0_1057
	s_waitcnt lgkmcnt(0)
	v_mov_b32_e32 v0, 0x2f83000
	global_load_dword v0, v0, s[58:59] offset:1280 sc1
	s_add_u32 s14, s58, 0x2f83500
	s_addc_u32 s15, s59, 0
	s_waitcnt vmcnt(0)
	v_cmp_eq_u32_e32 vcc, v0, v1
	s_and_saveexec_b64 s[10:11], vcc
	s_cbranch_execz .LBB0_1056
	s_add_u32 s12, s58, 0x2f80200
	s_addc_u32 s13, s59, 0
	s_mov_b32 s3, 1
	s_mov_b64 s[16:17], 0
	v_mov_b32_e32 v0, 0
	s_branch .LBB0_1047

; __device__ __forceinline__ unsigned xb_add(unsigned* p, unsigned v) { return __hip_atomic_fetch_add(p, v, __ATOMIC_RELAXED, __HIP_MEMORY_SCOPE_AGENT); }
; __device__ __forceinline__ void xcd_barrier(const XcdBarrier& b) {
;     ...
;             __builtin_amdgcn_fence(__ATOMIC_ACQUIRE, "agent");
;             xb_add(&bar[XB_XGEN(b.x)], 1u);
;             asm volatile("s_waitcnt vmcnt(0)" ::: "memory");
.LBB0_1074:
	s_or_b64 exec, exec, s[6:7]
	s_mov_b64 s[6:7], exec
	v_mbcnt_lo_u32_b32 v0, s6, 0
	v_mbcnt_hi_u32_b32 v0, s7, v0
	v_cmp_eq_u32_e32 vcc, 0, v0
	s_waitcnt vmcnt(0)
	buffer_inv sc1
	s_and_saveexec_b64 s[10:11], vcc
	s_cbranch_execz .LBB0_1076
	s_bcnt1_i32_b64 s3, s[6:7]
	v_mov_b32_e32 v0, 0x2000
	v_mov_b32_e32 v1, s3
.LBB0_1076:
	s_or_b64 exec, exec, s[10:11]
	s_waitcnt vmcnt(0)

; __device__ __forceinline__ unsigned xb_add(unsigned* p, unsigned v) { return __hip_atomic_fetch_add(p, v, __ATOMIC_RELAXED, __HIP_MEMORY_SCOPE_AGENT); }
; __device__ __forceinline__ void xcd_barrier(const XcdBarrier& b) {
;     ...
;             __builtin_amdgcn_fence(__ATOMIC_ACQUIRE, "agent");
;             xb_add(&bar[XB_XGEN(b.x)], 1u);
;             asm volatile("s_waitcnt vmcnt(0)" ::: "memory");
.LBB0_1129:
	s_or_b64 exec, exec, s[6:7]
	s_mov_b64 s[6:7], exec
	v_mbcnt_lo_u32_b32 v0, s6, 0
	v_mbcnt_hi_u32_b32 v0, s7, v0
	v_cmp_eq_u32_e32 vcc, 0, v0
	s_waitcnt vmcnt(0)
	buffer_inv sc1
	s_and_saveexec_b64 s[10:11], vcc
	s_cbranch_execz .LBB0_1131
	s_bcnt1_i32_b64 s3, s[6:7]
	v_mov_b32_e32 v0, 0x2000
	v_mov_b32_e32 v1, s3
.LBB0_1131:
	s_or_b64 exec, exec, s[10:11]
	s_waitcnt vmcnt(0)

; __device__ __forceinline__ unsigned xb_ld(unsigned* p)              { return __hip_atomic_load(p, __ATOMIC_RELAXED, __HIP_MEMORY_SCOPE_AGENT); }
; __device__ __forceinline__ unsigned xb_add(unsigned* p, unsigned v) { return __hip_atomic_fetch_add(p, v, __ATOMIC_RELAXED, __HIP_MEMORY_SCOPE_AGENT); }
; #define XB_SPIN(cond, bar) do { unsigned _sp = 0; while (cond) { __builtin_amdgcn_s_sleep(1); \
;     if ((++_sp & 255u) == 0u) { if (xb_ld(&(bar)[XB_TMO])) break; if (_sp > XB_SPIN_CAP) { atomicAdd(&(bar)[XB_TMO], 1u); break; } } } } while (0)
; __device__ __forceinline__ void xcd_barrier(const XcdBarrier& b) {
;     ...
;         const unsigned old = xb_add(&bar[XB_XSUB(b.x)], 1u);
;         const unsigned gen = old / nloc;
;         if (old + 1u == (gen + 1u) * nloc) {
;             __builtin_amdgcn_fence(__ATOMIC_RELEASE, "agent");
;             asm volatile("s_waitcnt vmcnt(0)" ::: "memory");
;             const unsigned og = xb_add(&bar[XB_TOP], 1u);
;             const unsigned tg = og / nx;
;             if (og + 1u == (tg + 1u) * nx) xb_add(&bar[XB_TOPGEN], 1u);
;             else XB_SPIN(xb_ld(&bar[XB_TOPGEN]) == tg, bar);
;             __builtin_amdgcn_fence(__ATOMIC_ACQUIRE, "agent");
;             xb_add(&bar[XB_XGEN(b.x)], 1u);
;             asm volatile("s_waitcnt vmcnt(0)" ::: "memory");
;         } else {
;             XB_SPIN(xb_ld(&bar[XB_XGEN(b.x)]) == gen, bar);
.LBB0_1188:
	s_or_b64 exec, exec, s[6:7]
	v_cvt_f32_u32_e32 v4, v2
	s_waitcnt vmcnt(0)
	v_readfirstlane_b32 s4, v3
	v_sub_u32_e32 v3, 0, v2
	v_rcp_iflag_f32_e32 v4, v4
	v_add_u32_e32 v5, s4, v1
	v_mul_f32_e32 v4, 0x4f7ffffe, v4
	v_cvt_u32_f32_e32 v4, v4
	v_mul_lo_u32 v1, v3, v4
	v_mul_hi_u32 v1, v4, v1
	v_add_u32_e32 v1, v4, v1
	v_mul_hi_u32 v1, v5, v1
	v_mul_lo_u32 v3, v1, v2
	v_sub_u32_e32 v3, v5, v3
	v_add_u32_e32 v4, 1, v1
	v_cmp_ge_u32_e32 vcc, v3, v2
	s_nop 1
	v_cndmask_b32_e32 v1, v1, v4, vcc
	v_sub_u32_e32 v4, v3, v2
	v_cndmask_b32_e32 v3, v3, v4, vcc
	v_add_u32_e32 v4, 1, v1
	v_cmp_ge_u32_e32 vcc, v3, v2
	v_add_u32_e32 v3, 1, v5
	s_nop 0
	v_cndmask_b32_e32 v1, v1, v4, vcc
	v_mul_lo_u32 v4, v2, v1
	v_add_u32_e32 v2, v4, v2
	v_cmp_ne_u32_e32 vcc, v3, v2
	s_and_saveexec_b64 s[4:5], vcc
	s_xor_b64 s[4:5], exec, s[4:5]
	s_cbranch_execz .LBB0_1202
	s_waitcnt lgkmcnt(0)
	v_mov_b32_e32 v0, 0x2f83000
	global_load_dword v0, v0, s[58:59] offset:1280 sc1
	s_add_u32 s10, s58, 0x2f83500
	s_addc_u32 s11, s59, 0
	s_waitcnt vmcnt(0)
	v_cmp_eq_u32_e32 vcc, v0, v1
	s_and_saveexec_b64 s[6:7], vcc
	s_cbranch_execz .LBB0_1201
	s_add_u32 s8, s58, 0x2f80200
	s_addc_u32 s9, s59, 0
	s_mov_b32 s22, 1
	s_mov_b64 s[12:13], 0
	v_mov_b32_e32 v0, 0
	s_branch .LBB0_1192

; __device__ __forceinline__ unsigned xb_add(unsigned* p, unsigned v) { return __hip_atomic_fetch_add(p, v, __ATOMIC_RELAXED, __HIP_MEMORY_SCOPE_AGENT); }
; __device__ __forceinline__ void xcd_barrier(const XcdBarrier& b) {
;     ...
;             __builtin_amdgcn_fence(__ATOMIC_ACQUIRE, "agent");
;             xb_add(&bar[XB_XGEN(b.x)], 1u);
;             asm volatile("s_waitcnt vmcnt(0)" ::: "memory");
.LBB0_1219:
	s_or_b64 exec, exec, s[4:5]
	s_mov_b64 s[4:5], exec
	v_mbcnt_lo_u32_b32 v0, s4, 0
	v_mbcnt_hi_u32_b32 v0, s5, v0
	v_cmp_eq_u32_e32 vcc, 0, v0
	s_waitcnt vmcnt(0)
	buffer_inv sc1
	s_and_saveexec_b64 s[6:7], vcc
	s_cbranch_execz .LBB0_1221
	s_bcnt1_i32_b64 s4, s[4:5]
	v_mov_b32_e32 v0, 0x2000
	v_mov_b32_e32 v1, s4
.LBB0_1221:
	s_or_b64 exec, exec, s[6:7]
	s_waitcnt vmcnt(0)
